# GEMM per-block s_setprio flips removed; one static s_setprio 1 for waves 4-7
# baseline (speedup 1.0000x reference)
.LBB0_18:
	v_readlane_b32 s0, v244, 47
	v_readlane_b32 s2, v244, 49
	v_readlane_b32 s1, v244, 48
	s_mov_b32 s6, s2
	s_lshr_b32 s88, s87, 6
	s_cmp_ge_u32 s88, 4
	s_cbranch_scc0 .Lprio_done
	s_setprio 1
.Lprio_done:
	s_mov_b64 s[4:5], s[0:1]
	s_cmp_lt_i32 s4, 1
	v_readlane_b32 s3, v244, 50
	s_cselect_b64 s[0:1], -1, 0
	s_cmp_gt_i32 s5, 0
	s_cselect_b64 s[2:3], -1, 0
	s_and_b64 s[2:3], s[0:1], s[2:3]
	s_andn2_b64 vcc, exec, s[2:3]
	v_and_b32_e32 v144, 63, v182
	s_cbranch_vccnz .LBB0_324
	s_lshl_b32 s0, s89, 3
	v_readlane_b32 s36, v244, 0
	s_add_i32 s6, s88, s0
	s_lshl_b32 s24, s86, 3
	v_readlane_b32 s42, v244, 6
	v_readlane_b32 s43, v244, 7
	s_add_u32 s4, s42, 0x18000000
	s_addc_u32 s5, s43, 0
	s_cmpk_gt_i32 s6, 0x1fff
	v_readlane_b32 s37, v244, 1
	v_readlane_b32 s38, v244, 2
	v_readlane_b32 s39, v244, 3
	v_readlane_b32 s40, v244, 4
	v_readlane_b32 s41, v244, 5
	s_cbranch_scc1 .LBB0_276
	s_lshl_b32 s0, s88, 14
	v_lshlrev_b32_e32 v1, 4, v182
	s_add_i32 s7, s0, 0
	v_lshrrev_b32_e32 v0, 3, v144
	v_and_b32_e32 v30, 0x70, v1
	s_movk_i32 s0, 0x84
	v_mov_b32_e32 v1, 0x420
	v_mad_u32_u24 v41, v0, s0, v1
	v_mov_b32_e32 v1, 0x840
	v_mad_u32_u24 v43, v0, s0, v1
	v_mov_b32_e32 v1, 0xc60
	v_mad_u32_u24 v45, v0, s0, v1
	v_lshlrev_b32_e32 v1, 3, v182
	v_and_b32_e32 v1, 56, v1
	v_readlane_b32 s36, v244, 0
	v_lshlrev_b32_e32 v2, 1, v1
	v_mov_b32_e32 v3, 0
	v_readlane_b32 s42, v244, 6
	v_readlane_b32 s43, v244, 7
	v_readlane_b32 s37, v244, 1
	v_readlane_b32 s38, v244, 2
	v_readlane_b32 s39, v244, 3
	v_readlane_b32 s40, v244, 4
	v_readlane_b32 s41, v244, 5
	v_lshl_add_u64 v[14:15], s[42:43], 0, v[2:3]
	s_mov_b64 s[0:1], 0x1e800000
	v_mov_b32_e32 v31, v3
	v_mul_u32_u24_e32 v6, 0x84, v1
	v_lshl_add_u64 v[4:5], v[14:15], 0, s[0:1]
	v_lshlrev_b32_e32 v1, 2, v0
	s_mov_b64 s[0:1], 0x1e000000
	v_lshl_add_u64 v[18:19], s[38:39], 0, v[30:31]
	v_lshl_add_u64 v[20:21], s[36:37], 0, v[30:31]
	v_readlane_b32 s36, v244, 31
	v_add3_u32 v50, s7, v6, v1
	v_lshl_add_u64 v[6:7], v[14:15], 0, s[0:1]
	s_mov_b64 s[0:1], 0x1f800000
	v_readlane_b32 s50, v244, 45
	v_readlane_b32 s51, v244, 46
	v_lshl_add_u64 v[8:9], v[14:15], 0, s[0:1]
	s_mov_b64 s[0:1], 0x1f400000
	v_readlane_b32 s37, v244, 32
	v_readlane_b32 s52, v244, 15
	s_cmp_lg_u64 s[50:51], 0
	v_lshl_add_u64 v[10:11], v[14:15], 0, s[0:1]
	s_mov_b64 s[0:1], 0x1f200000
	v_readlane_b32 s58, v244, 21
	v_readlane_b32 s59, v244, 22
	s_cselect_b64 s[26:27], -1, 0
	s_cmp_lg_u64 s[36:37], 0
	v_lshl_add_u64 v[12:13], v[14:15], 0, s[0:1]
	s_mov_b64 s[0:1], 0x1f000000
	v_readlane_b32 s40, v244, 35
	v_readlane_b32 s41, v244, 36
	v_readlane_b32 s42, v244, 37
	v_readlane_b32 s43, v244, 38
	v_readlane_b32 s48, v244, 43
	v_readlane_b32 s49, v244, 44
	v_readlane_b32 s66, v244, 29
	v_readlane_b32 s67, v244, 30
	s_cselect_b64 s[28:29], -1, 0
	s_cmp_lg_u64 s[58:59], 0
	v_add_u32_e32 v39, s7, v30
	v_mul_u32_u24_e32 v34, 0x84, v0
	v_lshl_add_u64 v[14:15], v[14:15], 0, s[0:1]
	v_lshl_add_u64 v[22:23], s[48:49], 0, v[30:31]
	v_lshl_add_u64 v[24:25], s[42:43], 0, v[30:31]
	v_lshl_add_u64 v[26:27], s[40:41], 0, v[30:31]
	v_lshl_add_u64 v[28:29], s[66:67], 0, v[30:31]
	v_lshl_add_u64 v[30:31], s[18:19], 0, v[30:31]
	s_cselect_b64 s[30:31], -1, 0
	s_cmp_lg_u64 s[16:17], 0
	s_mov_b64 s[0:1], 0x1840
	v_readlane_b32 s44, v244, 39
	v_readlane_b32 s45, v244, 40
	v_readlane_b32 s46, v244, 41
	v_readlane_b32 s47, v244, 42
	s_cselect_b64 s[34:35], -1, 0
	v_lshl_add_u64 v[32:33], v[30:31], 0, s[0:1]
	s_lshl_b32 s0, s6, 1
	v_add_u32_e32 v51, v39, v34
	v_or_b32_e32 v40, 8, v0
	v_or_b32_e32 v42, 16, v0
	v_or_b32_e32 v44, 24, v0
	v_or_b32_e32 v46, 32, v0
	v_or_b32_e32 v47, 40, v0
	v_or_b32_e32 v48, 48, v0
	v_or_b32_e32 v49, 56, v0
	v_lshl_add_u64 v[16:17], s[4:5], 0, v[2:3]
	v_mov_b32_e32 v1, v3
	s_lshl_b32 s7, s6, 5
	s_lshl_b32 s25, s86, 8
	s_add_i32 s33, s0, 0x1d000
	s_lshl_b32 s44, s86, 4
	v_add_u32_e32 v52, 0x420, v51
	v_add_u32_e32 v53, 0x428, v51
	v_add_u32_e32 v54, 0x840, v51
	s_movk_i32 s45, 0x1ff
	s_movk_i32 s46, 0x3040
	v_add_u32_e32 v55, 0x848, v51
	v_add_u32_e32 v56, 0xc60, v51
	v_add_u32_e32 v57, 0xc68, v51
	s_mov_b32 s47, s6
	s_mov_b32 s37, 0
	v_readlane_b32 s38, v244, 33
	v_readlane_b32 s39, v244, 34
	v_readlane_b32 s53, v244, 16
	v_readlane_b32 s54, v244, 17
	v_readlane_b32 s55, v244, 18
	v_readlane_b32 s56, v244, 19
	v_readlane_b32 s57, v244, 20
	v_readlane_b32 s60, v244, 23
	v_readlane_b32 s61, v244, 24
	v_readlane_b32 s62, v244, 25
	v_readlane_b32 s63, v244, 26
	v_readlane_b32 s64, v244, 27
	v_readlane_b32 s65, v244, 28
	s_branch .LBB0_24

.LBB0_398:
	ds_read_b128 v[158:161], v154
	ds_read_b128 v[162:165], v154 offset:1024
	ds_read_b128 v[166:169], v154 offset:2048
	ds_read_b128 v[170:173], v154 offset:3072
	ds_read_b128 v[174:177], v155
	ds_read_b128 v[178:181], v155 offset:1024
	ds_read_b128 v[184:187], v155 offset:2048
	ds_read_b128 v[188:191], v155 offset:3072
	s_add_u32 s34, s30, 0xfffc0080
	s_addc_u32 s35, s31, -1
	s_cmp_eq_u32 s55, 12
	s_cselect_b32 s37, s5, s35
	s_cselect_b32 s36, s8, s34
	s_cselect_b32 s35, s19, s54
	s_cselect_b32 s34, s25, s53
	v_lshl_add_u64 v[152:153], s[30:31], 0, v[142:143]
	s_add_i32 m0, s7, 0xc000
	ds_read_b128 v[192:195], v156
	ds_read_b128 v[196:199], v156 offset:1024
	ds_read_b128 v[200:203], v156 offset:2048
	ds_read_b128 v[204:207], v156 offset:3072
	ds_read_b128 v[208:211], v156 offset:4096
	ds_read_b128 v[212:215], v156 offset:5120
	ds_read_b128 v[216:219], v156 offset:6144
	ds_read_b128 v[220:223], v156 offset:7168
	global_load_lds_dwordx4 v[152:153], off
	v_lshl_add_u64 v[152:153], s[30:31], 0, v[146:147]
	s_add_i32 m0, s7, 0xe000
	s_nop 0
	global_load_lds_dwordx4 v[152:153], off
	s_waitcnt vmcnt(8)
	s_waitcnt lgkmcnt(0)
	s_barrier
	s_waitcnt lgkmcnt(0)
	v_mfma_f32_16x16x32_bf16 v[124:127], v[158:161], v[192:195], v[124:127]
	v_mfma_f32_16x16x32_bf16 v[120:123], v[166:169], v[192:195], v[120:123]
	v_mfma_f32_16x16x32_bf16 v[108:111], v[158:161], v[200:203], v[108:111]
	v_mfma_f32_16x16x32_bf16 v[104:107], v[166:169], v[200:203], v[104:107]
	v_mfma_f32_16x16x32_bf16 v[92:95], v[158:161], v[208:211], v[92:95]
	v_mfma_f32_16x16x32_bf16 v[88:91], v[166:169], v[208:211], v[88:91]
	v_mfma_f32_16x16x32_bf16 v[76:79], v[158:161], v[216:219], v[76:79]
	v_mfma_f32_16x16x32_bf16 v[72:75], v[166:169], v[216:219], v[72:75]
	v_mfma_f32_16x16x32_bf16 v[124:127], v[162:165], v[196:199], v[124:127]
	v_mfma_f32_16x16x32_bf16 v[120:123], v[170:173], v[196:199], v[120:123]
	v_mfma_f32_16x16x32_bf16 v[108:111], v[162:165], v[204:207], v[108:111]
	v_mfma_f32_16x16x32_bf16 v[104:107], v[170:173], v[204:207], v[104:107]
	v_mfma_f32_16x16x32_bf16 v[92:95], v[162:165], v[212:215], v[92:95]
	v_mfma_f32_16x16x32_bf16 v[88:91], v[170:173], v[212:215], v[88:91]
	v_mfma_f32_16x16x32_bf16 v[76:79], v[162:165], v[220:223], v[76:79]
	v_mfma_f32_16x16x32_bf16 v[72:75], v[170:173], v[220:223], v[72:75]
	v_mfma_f32_16x16x32_bf16 v[116:119], v[174:177], v[192:195], v[116:119]
	v_mfma_f32_16x16x32_bf16 v[112:115], v[184:187], v[192:195], v[112:115]
	v_mfma_f32_16x16x32_bf16 v[100:103], v[174:177], v[200:203], v[100:103]
	v_mfma_f32_16x16x32_bf16 v[96:99], v[184:187], v[200:203], v[96:99]
	v_mfma_f32_16x16x32_bf16 v[84:87], v[174:177], v[208:211], v[84:87]
	v_mfma_f32_16x16x32_bf16 v[80:83], v[184:187], v[208:211], v[80:83]
	v_mfma_f32_16x16x32_bf16 v[68:71], v[174:177], v[216:219], v[68:71]
	v_mfma_f32_16x16x32_bf16 v[64:67], v[184:187], v[216:219], v[64:67]
	v_mfma_f32_16x16x32_bf16 v[116:119], v[178:181], v[196:199], v[116:119]
	v_mfma_f32_16x16x32_bf16 v[112:115], v[188:191], v[196:199], v[112:115]
	v_mfma_f32_16x16x32_bf16 v[100:103], v[178:181], v[204:207], v[100:103]
	v_mfma_f32_16x16x32_bf16 v[96:99], v[188:191], v[204:207], v[96:99]
	v_mfma_f32_16x16x32_bf16 v[84:87], v[178:181], v[212:215], v[84:87]
	v_mfma_f32_16x16x32_bf16 v[80:83], v[188:191], v[212:215], v[80:83]
	v_mfma_f32_16x16x32_bf16 v[68:71], v[178:181], v[220:223], v[68:71]
	v_mfma_f32_16x16x32_bf16 v[64:67], v[188:191], v[220:223], v[64:67]
	s_barrier
	s_add_i32 s56, s50, s39
	v_lshl_add_u64 v[152:153], s[34:35], 0, v[130:131]
	s_mov_b32 m0, s56
	ds_read_b128 v[192:195], v156 offset:16384
	ds_read_b128 v[196:199], v156 offset:17408
	ds_read_b128 v[200:203], v156 offset:18432
	ds_read_b128 v[204:207], v156 offset:19456
	ds_read_b128 v[208:211], v156 offset:20480
	ds_read_b128 v[212:215], v156 offset:21504
	ds_read_b128 v[216:219], v156 offset:22528
	ds_read_b128 v[220:223], v156 offset:23552
	global_load_lds_dwordx4 v[152:153], off
	s_add_i32 m0, s56, 0x2000
	s_add_u32 s56, s34, 0x40000
	v_lshl_add_u64 v[224:225], s[34:35], 0, v[134:135]
	s_addc_u32 s57, s35, 0
	s_add_i32 s58, s51, s39
	global_load_lds_dwordx4 v[224:225], off
	v_lshl_add_u64 v[226:227], s[56:57], 0, v[130:131]
	s_mov_b32 m0, s58
	v_lshl_add_u64 v[228:229], s[36:37], 0, v[132:133]
	global_load_lds_dwordx4 v[226:227], off
	v_lshl_add_u64 v[226:227], s[56:57], 0, v[134:135]
	s_add_i32 m0, s58, 0x2000
	s_nop 0
	global_load_lds_dwordx4 v[226:227], off
	v_lshl_add_u64 v[226:227], s[36:37], 0, v[128:129]
	s_mov_b32 m0, s7
	s_nop 0
	global_load_lds_dwordx4 v[226:227], off
	s_mov_b32 m0, s40
	s_nop 0
	global_load_lds_dwordx4 v[228:229], off
	s_waitcnt vmcnt(8)
	s_waitcnt lgkmcnt(0)
	s_barrier
	s_waitcnt lgkmcnt(0)
	v_mfma_f32_16x16x32_bf16 v[60:63], v[158:161], v[192:195], v[60:63]
	v_mfma_f32_16x16x32_bf16 v[56:59], v[166:169], v[192:195], v[56:59]
	v_mfma_f32_16x16x32_bf16 v[44:47], v[158:161], v[200:203], v[44:47]
	v_mfma_f32_16x16x32_bf16 v[40:43], v[166:169], v[200:203], v[40:43]
	v_mfma_f32_16x16x32_bf16 v[28:31], v[158:161], v[208:211], v[28:31]
	v_mfma_f32_16x16x32_bf16 v[24:27], v[166:169], v[208:211], v[24:27]
	v_mfma_f32_16x16x32_bf16 v[12:15], v[158:161], v[216:219], v[12:15]
	v_mfma_f32_16x16x32_bf16 v[8:11], v[166:169], v[216:219], v[8:11]
	v_mfma_f32_16x16x32_bf16 v[60:63], v[162:165], v[196:199], v[60:63]
	v_mfma_f32_16x16x32_bf16 v[56:59], v[170:173], v[196:199], v[56:59]
	v_mfma_f32_16x16x32_bf16 v[44:47], v[162:165], v[204:207], v[44:47]
	v_mfma_f32_16x16x32_bf16 v[40:43], v[170:173], v[204:207], v[40:43]
	v_mfma_f32_16x16x32_bf16 v[28:31], v[162:165], v[212:215], v[28:31]
	v_mfma_f32_16x16x32_bf16 v[24:27], v[170:173], v[212:215], v[24:27]
	v_mfma_f32_16x16x32_bf16 v[12:15], v[162:165], v[220:223], v[12:15]
	v_mfma_f32_16x16x32_bf16 v[8:11], v[170:173], v[220:223], v[8:11]
	v_mfma_f32_16x16x32_bf16 v[52:55], v[174:177], v[192:195], v[52:55]
	v_mfma_f32_16x16x32_bf16 v[48:51], v[184:187], v[192:195], v[48:51]
	v_mfma_f32_16x16x32_bf16 v[36:39], v[174:177], v[200:203], v[36:39]
	v_mfma_f32_16x16x32_bf16 v[32:35], v[184:187], v[200:203], v[32:35]
	v_mfma_f32_16x16x32_bf16 v[20:23], v[174:177], v[208:211], v[20:23]
	v_mfma_f32_16x16x32_bf16 v[16:19], v[184:187], v[208:211], v[16:19]
	v_mfma_f32_16x16x32_bf16 v[4:7], v[174:177], v[216:219], v[4:7]
	v_mfma_f32_16x16x32_bf16 v[0:3], v[184:187], v[216:219], v[0:3]
	v_mfma_f32_16x16x32_bf16 v[52:55], v[178:181], v[196:199], v[52:55]
	v_mfma_f32_16x16x32_bf16 v[48:51], v[188:191], v[196:199], v[48:51]
	v_mfma_f32_16x16x32_bf16 v[36:39], v[178:181], v[204:207], v[36:39]
	v_mfma_f32_16x16x32_bf16 v[32:35], v[188:191], v[204:207], v[32:35]
	v_mfma_f32_16x16x32_bf16 v[20:23], v[178:181], v[212:215], v[20:23]
	v_mfma_f32_16x16x32_bf16 v[16:19], v[188:191], v[212:215], v[16:19]
	v_mfma_f32_16x16x32_bf16 v[4:7], v[178:181], v[220:223], v[4:7]
	v_mfma_f32_16x16x32_bf16 v[0:3], v[188:191], v[220:223], v[0:3]
	s_barrier
	s_add_i32 s56, 0, 0x18000
	v_add_u32_e32 v136, s56, v145
	s_add_i32 s57, 0, 0x1c000
	ds_read_b128 v[158:161], v136
	ds_read_b128 v[162:165], v136 offset:1024
	ds_read_b128 v[166:169], v136 offset:2048
	ds_read_b128 v[170:173], v136 offset:3072
	v_add_u32_e32 v136, s57, v145
	ds_read_b128 v[174:177], v136
	ds_read_b128 v[178:181], v136 offset:1024
	ds_read_b128 v[184:187], v136 offset:2048
	ds_read_b128 v[188:191], v136 offset:3072
	s_add_u32 s36, s36, 0x40000
	s_addc_u32 s37, s37, 0
	s_mov_b32 m0, s41
	v_lshl_add_u64 v[230:231], s[36:37], 0, v[128:129]
	ds_read_b128 v[192:195], v156 offset:32768
	ds_read_b128 v[196:199], v156 offset:33792
	ds_read_b128 v[200:203], v156 offset:34816
	ds_read_b128 v[204:207], v156 offset:35840
	ds_read_b128 v[208:211], v156 offset:36864
	ds_read_b128 v[212:215], v156 offset:37888
	ds_read_b128 v[216:219], v156 offset:38912
	ds_read_b128 v[220:223], v156 offset:39936
	global_load_lds_dwordx4 v[230:231], off
	v_lshl_add_u64 v[230:231], s[36:37], 0, v[132:133]
	s_mov_b32 m0, s42
	s_nop 0
	global_load_lds_dwordx4 v[230:231], off
	s_waitcnt vmcnt(8)
	s_waitcnt lgkmcnt(0)
	s_barrier
	s_waitcnt lgkmcnt(0)
	v_mfma_f32_16x16x32_bf16 v[124:127], v[158:161], v[192:195], v[124:127]
	v_mfma_f32_16x16x32_bf16 v[120:123], v[166:169], v[192:195], v[120:123]
	v_mfma_f32_16x16x32_bf16 v[108:111], v[158:161], v[200:203], v[108:111]
	v_mfma_f32_16x16x32_bf16 v[104:107], v[166:169], v[200:203], v[104:107]
	v_mfma_f32_16x16x32_bf16 v[92:95], v[158:161], v[208:211], v[92:95]
	v_mfma_f32_16x16x32_bf16 v[88:91], v[166:169], v[208:211], v[88:91]
	v_mfma_f32_16x16x32_bf16 v[76:79], v[158:161], v[216:219], v[76:79]
	v_mfma_f32_16x16x32_bf16 v[72:75], v[166:169], v[216:219], v[72:75]
	v_mfma_f32_16x16x32_bf16 v[124:127], v[162:165], v[196:199], v[124:127]
	v_mfma_f32_16x16x32_bf16 v[120:123], v[170:173], v[196:199], v[120:123]
	v_mfma_f32_16x16x32_bf16 v[108:111], v[162:165], v[204:207], v[108:111]
	v_mfma_f32_16x16x32_bf16 v[104:107], v[170:173], v[204:207], v[104:107]
	v_mfma_f32_16x16x32_bf16 v[92:95], v[162:165], v[212:215], v[92:95]
	v_mfma_f32_16x16x32_bf16 v[88:91], v[170:173], v[212:215], v[88:91]
	v_mfma_f32_16x16x32_bf16 v[76:79], v[162:165], v[220:223], v[76:79]
	v_mfma_f32_16x16x32_bf16 v[72:75], v[170:173], v[220:223], v[72:75]
	v_mfma_f32_16x16x32_bf16 v[116:119], v[174:177], v[192:195], v[116:119]
	v_mfma_f32_16x16x32_bf16 v[112:115], v[184:187], v[192:195], v[112:115]
	v_mfma_f32_16x16x32_bf16 v[100:103], v[174:177], v[200:203], v[100:103]
	v_mfma_f32_16x16x32_bf16 v[96:99], v[184:187], v[200:203], v[96:99]
	v_mfma_f32_16x16x32_bf16 v[84:87], v[174:177], v[208:211], v[84:87]
	v_mfma_f32_16x16x32_bf16 v[80:83], v[184:187], v[208:211], v[80:83]
	v_mfma_f32_16x16x32_bf16 v[68:71], v[174:177], v[216:219], v[68:71]
	v_mfma_f32_16x16x32_bf16 v[64:67], v[184:187], v[216:219], v[64:67]
	v_mfma_f32_16x16x32_bf16 v[116:119], v[178:181], v[196:199], v[116:119]
	v_mfma_f32_16x16x32_bf16 v[112:115], v[188:191], v[196:199], v[112:115]
	v_mfma_f32_16x16x32_bf16 v[100:103], v[178:181], v[204:207], v[100:103]
	v_mfma_f32_16x16x32_bf16 v[96:99], v[188:191], v[204:207], v[96:99]
	v_mfma_f32_16x16x32_bf16 v[84:87], v[178:181], v[212:215], v[84:87]
	v_mfma_f32_16x16x32_bf16 v[80:83], v[188:191], v[212:215], v[80:83]
	v_mfma_f32_16x16x32_bf16 v[68:71], v[178:181], v[220:223], v[68:71]
	v_mfma_f32_16x16x32_bf16 v[64:67], v[188:191], v[220:223], v[64:67]
	s_barrier
	s_add_i32 s36, s56, s39
	v_lshl_add_u64 v[152:153], v[152:153], 0, s[12:13]
	s_mov_b32 m0, s36
	ds_read_b128 v[192:195], v156 offset:49152
	ds_read_b128 v[196:199], v156 offset:50176
	ds_read_b128 v[200:203], v156 offset:51200
	ds_read_b128 v[204:207], v156 offset:52224
	ds_read_b128 v[208:211], v156 offset:53248
	ds_read_b128 v[212:215], v156 offset:54272
	ds_read_b128 v[216:219], v156 offset:55296
	ds_read_b128 v[220:223], v156 offset:56320
	global_load_lds_dwordx4 v[152:153], off
	s_add_i32 m0, s36, 0x2000
	s_add_u32 s34, s34, 0x40080
	v_lshl_add_u64 v[152:153], v[224:225], 0, s[12:13]
	s_addc_u32 s35, s35, 0
	s_add_i32 s36, s57, s39
	global_load_lds_dwordx4 v[152:153], off
	v_lshl_add_u64 v[152:153], s[34:35], 0, v[130:131]
	s_mov_b32 m0, s36
	s_nop 0
	global_load_lds_dwordx4 v[152:153], off
	v_lshl_add_u64 v[152:153], s[34:35], 0, v[134:135]
	s_add_i32 m0, s36, 0x2000
	s_nop 0
	global_load_lds_dwordx4 v[152:153], off
	v_lshl_add_u64 v[152:153], v[226:227], 0, s[12:13]
	s_mov_b32 m0, s45
	s_nop 0
	global_load_lds_dwordx4 v[152:153], off
	v_lshl_add_u64 v[152:153], v[228:229], 0, s[12:13]
	s_mov_b32 m0, s46
	s_nop 0
	global_load_lds_dwordx4 v[152:153], off
	s_waitcnt vmcnt(8)
	s_waitcnt lgkmcnt(0)
	s_barrier
	s_waitcnt lgkmcnt(0)
	v_mfma_f32_16x16x32_bf16 v[60:63], v[158:161], v[192:195], v[60:63]
	v_mfma_f32_16x16x32_bf16 v[56:59], v[166:169], v[192:195], v[56:59]
	v_mfma_f32_16x16x32_bf16 v[44:47], v[158:161], v[200:203], v[44:47]
	v_mfma_f32_16x16x32_bf16 v[40:43], v[166:169], v[200:203], v[40:43]
	v_mfma_f32_16x16x32_bf16 v[28:31], v[158:161], v[208:211], v[28:31]
	v_mfma_f32_16x16x32_bf16 v[24:27], v[166:169], v[208:211], v[24:27]
	v_mfma_f32_16x16x32_bf16 v[12:15], v[158:161], v[216:219], v[12:15]
	v_mfma_f32_16x16x32_bf16 v[8:11], v[166:169], v[216:219], v[8:11]
	v_mfma_f32_16x16x32_bf16 v[60:63], v[162:165], v[196:199], v[60:63]
	v_mfma_f32_16x16x32_bf16 v[56:59], v[170:173], v[196:199], v[56:59]
	v_mfma_f32_16x16x32_bf16 v[44:47], v[162:165], v[204:207], v[44:47]
	v_mfma_f32_16x16x32_bf16 v[40:43], v[170:173], v[204:207], v[40:43]
	v_mfma_f32_16x16x32_bf16 v[28:31], v[162:165], v[212:215], v[28:31]
	v_mfma_f32_16x16x32_bf16 v[24:27], v[170:173], v[212:215], v[24:27]
	v_mfma_f32_16x16x32_bf16 v[12:15], v[162:165], v[220:223], v[12:15]
	v_mfma_f32_16x16x32_bf16 v[8:11], v[170:173], v[220:223], v[8:11]
	v_mfma_f32_16x16x32_bf16 v[52:55], v[174:177], v[192:195], v[52:55]
	v_mfma_f32_16x16x32_bf16 v[48:51], v[184:187], v[192:195], v[48:51]
	v_mfma_f32_16x16x32_bf16 v[36:39], v[174:177], v[200:203], v[36:39]
	v_mfma_f32_16x16x32_bf16 v[32:35], v[184:187], v[200:203], v[32:35]
	v_mfma_f32_16x16x32_bf16 v[20:23], v[174:177], v[208:211], v[20:23]
	v_mfma_f32_16x16x32_bf16 v[16:19], v[184:187], v[208:211], v[16:19]
	v_mfma_f32_16x16x32_bf16 v[4:7], v[174:177], v[216:219], v[4:7]
	v_mfma_f32_16x16x32_bf16 v[0:3], v[184:187], v[216:219], v[0:3]
	v_mfma_f32_16x16x32_bf16 v[52:55], v[178:181], v[196:199], v[52:55]
	v_mfma_f32_16x16x32_bf16 v[48:51], v[188:191], v[196:199], v[48:51]
	v_mfma_f32_16x16x32_bf16 v[36:39], v[178:181], v[204:207], v[36:39]
	v_mfma_f32_16x16x32_bf16 v[32:35], v[188:191], v[204:207], v[32:35]
	v_mfma_f32_16x16x32_bf16 v[20:23], v[178:181], v[212:215], v[20:23]
	v_mfma_f32_16x16x32_bf16 v[16:19], v[188:191], v[212:215], v[16:19]
	v_mfma_f32_16x16x32_bf16 v[4:7], v[178:181], v[220:223], v[4:7]
	v_mfma_f32_16x16x32_bf16 v[0:3], v[188:191], v[220:223], v[0:3]
	s_barrier
	s_add_i32 s55, s55, 2
	s_add_u32 s30, s30, 0x100
	s_addc_u32 s31, s31, 0
	s_add_u32 s53, s53, 0x100
	s_addc_u32 s54, s54, 0
	s_cmp_gt_u32 s55, 13
	s_cbranch_scc0 .LBB0_398
	s_and_b64 vcc, exec, s[14:15]
	s_cbranch_vccz .LBB0_401
	s_barrier

.LBB0_1489:
	ds_read_b128 v[158:161], v154
	ds_read_b128 v[162:165], v154 offset:1024
	ds_read_b128 v[166:169], v154 offset:2048
	ds_read_b128 v[170:173], v154 offset:3072
	ds_read_b128 v[174:177], v155
	ds_read_b128 v[178:181], v155 offset:1024
	ds_read_b128 v[184:187], v155 offset:2048
	ds_read_b128 v[188:191], v155 offset:3072
	s_add_u32 s34, s30, 0xfffc0080
	s_addc_u32 s35, s31, -1
	s_cmp_eq_u32 s65, 12
	s_cselect_b32 s37, s23, s35
	s_cselect_b32 s36, s61, s34
	s_cselect_b32 s35, s19, s64
	s_cselect_b32 s34, s62, s63
	v_lshl_add_u64 v[224:225], s[30:31], 0, v[138:139]
	s_add_i32 m0, s47, 0xc000
	ds_read_b128 v[192:195], v156
	ds_read_b128 v[196:199], v156 offset:1024
	ds_read_b128 v[200:203], v156 offset:2048
	ds_read_b128 v[204:207], v156 offset:3072
	ds_read_b128 v[208:211], v156 offset:4096
	ds_read_b128 v[212:215], v156 offset:5120
	ds_read_b128 v[216:219], v156 offset:6144
	ds_read_b128 v[220:223], v156 offset:7168
	global_load_lds_dwordx4 v[224:225], off
	v_lshl_add_u64 v[224:225], s[30:31], 0, v[140:141]
	s_add_i32 m0, s47, 0xe000
	s_nop 0
	global_load_lds_dwordx4 v[224:225], off
	s_waitcnt vmcnt(8)
	s_waitcnt lgkmcnt(0)
	s_barrier
	s_waitcnt lgkmcnt(0)
	v_mfma_f32_16x16x32_bf16 v[124:127], v[158:161], v[192:195], v[124:127]
	v_mfma_f32_16x16x32_bf16 v[120:123], v[166:169], v[192:195], v[120:123]
	v_mfma_f32_16x16x32_bf16 v[116:119], v[158:161], v[200:203], v[116:119]
	v_mfma_f32_16x16x32_bf16 v[108:111], v[166:169], v[200:203], v[108:111]
	v_mfma_f32_16x16x32_bf16 v[100:103], v[158:161], v[208:211], v[100:103]
	v_mfma_f32_16x16x32_bf16 v[92:95], v[166:169], v[208:211], v[92:95]
	v_mfma_f32_16x16x32_bf16 v[84:87], v[158:161], v[216:219], v[84:87]
	v_mfma_f32_16x16x32_bf16 v[76:79], v[166:169], v[216:219], v[76:79]
	v_mfma_f32_16x16x32_bf16 v[124:127], v[162:165], v[196:199], v[124:127]
	v_mfma_f32_16x16x32_bf16 v[120:123], v[170:173], v[196:199], v[120:123]
	v_mfma_f32_16x16x32_bf16 v[116:119], v[162:165], v[204:207], v[116:119]
	v_mfma_f32_16x16x32_bf16 v[108:111], v[170:173], v[204:207], v[108:111]
	v_mfma_f32_16x16x32_bf16 v[100:103], v[162:165], v[212:215], v[100:103]
	v_mfma_f32_16x16x32_bf16 v[92:95], v[170:173], v[212:215], v[92:95]
	v_mfma_f32_16x16x32_bf16 v[84:87], v[162:165], v[220:223], v[84:87]
	v_mfma_f32_16x16x32_bf16 v[76:79], v[170:173], v[220:223], v[76:79]
	v_mfma_f32_16x16x32_bf16 v[112:115], v[174:177], v[192:195], v[112:115]
	v_mfma_f32_16x16x32_bf16 v[104:107], v[184:187], v[192:195], v[104:107]
	v_mfma_f32_16x16x32_bf16 v[96:99], v[174:177], v[200:203], v[96:99]
	v_mfma_f32_16x16x32_bf16 v[88:91], v[184:187], v[200:203], v[88:91]
	v_mfma_f32_16x16x32_bf16 v[80:83], v[174:177], v[208:211], v[80:83]
	v_mfma_f32_16x16x32_bf16 v[72:75], v[184:187], v[208:211], v[72:75]
	v_mfma_f32_16x16x32_bf16 v[68:71], v[174:177], v[216:219], v[68:71]
	v_mfma_f32_16x16x32_bf16 v[64:67], v[184:187], v[216:219], v[64:67]
	v_mfma_f32_16x16x32_bf16 v[112:115], v[178:181], v[196:199], v[112:115]
	v_mfma_f32_16x16x32_bf16 v[104:107], v[188:191], v[196:199], v[104:107]
	v_mfma_f32_16x16x32_bf16 v[96:99], v[178:181], v[204:207], v[96:99]
	v_mfma_f32_16x16x32_bf16 v[88:91], v[188:191], v[204:207], v[88:91]
	v_mfma_f32_16x16x32_bf16 v[80:83], v[178:181], v[212:215], v[80:83]
	v_mfma_f32_16x16x32_bf16 v[72:75], v[188:191], v[212:215], v[72:75]
	v_mfma_f32_16x16x32_bf16 v[68:71], v[178:181], v[220:223], v[68:71]
	v_mfma_f32_16x16x32_bf16 v[64:67], v[188:191], v[220:223], v[64:67]
	s_barrier
	s_add_i32 s66, s55, s45
	v_lshl_add_u64 v[224:225], s[34:35], 0, v[130:131]
	s_mov_b32 m0, s66
	ds_read_b128 v[192:195], v156 offset:16384
	ds_read_b128 v[196:199], v156 offset:17408
	ds_read_b128 v[200:203], v156 offset:18432
	ds_read_b128 v[204:207], v156 offset:19456
	ds_read_b128 v[208:211], v156 offset:20480
	ds_read_b128 v[212:215], v156 offset:21504
	ds_read_b128 v[216:219], v156 offset:22528
	ds_read_b128 v[220:223], v156 offset:23552
	global_load_lds_dwordx4 v[224:225], off
	s_add_i32 m0, s66, 0x2000
	s_add_u32 s66, s34, 0x40000
	v_lshl_add_u64 v[226:227], s[34:35], 0, v[134:135]
	s_addc_u32 s67, s35, 0
	s_add_i32 s68, s56, s45
	global_load_lds_dwordx4 v[226:227], off
	v_lshl_add_u64 v[228:229], s[66:67], 0, v[130:131]
	s_mov_b32 m0, s68
	v_lshl_add_u64 v[230:231], s[36:37], 0, v[132:133]
	global_load_lds_dwordx4 v[228:229], off
	v_lshl_add_u64 v[228:229], s[66:67], 0, v[134:135]
	s_add_i32 m0, s68, 0x2000
	s_nop 0
	global_load_lds_dwordx4 v[228:229], off
	v_lshl_add_u64 v[228:229], s[36:37], 0, v[128:129]
	s_mov_b32 m0, s47
	s_nop 0
	global_load_lds_dwordx4 v[228:229], off
	s_mov_b32 m0, s48
	s_nop 0
	global_load_lds_dwordx4 v[230:231], off
	s_waitcnt vmcnt(8)
	s_waitcnt lgkmcnt(0)
	s_barrier
	s_waitcnt lgkmcnt(0)
	v_mfma_f32_16x16x32_bf16 v[60:63], v[158:161], v[192:195], v[60:63]
	v_mfma_f32_16x16x32_bf16 v[56:59], v[166:169], v[192:195], v[56:59]
	v_mfma_f32_16x16x32_bf16 v[52:55], v[158:161], v[200:203], v[52:55]
	v_mfma_f32_16x16x32_bf16 v[44:47], v[166:169], v[200:203], v[44:47]
	v_mfma_f32_16x16x32_bf16 v[36:39], v[158:161], v[208:211], v[36:39]
	v_mfma_f32_16x16x32_bf16 v[28:31], v[166:169], v[208:211], v[28:31]
	v_mfma_f32_16x16x32_bf16 v[20:23], v[158:161], v[216:219], v[20:23]
	v_mfma_f32_16x16x32_bf16 v[12:15], v[166:169], v[216:219], v[12:15]
	v_mfma_f32_16x16x32_bf16 v[60:63], v[162:165], v[196:199], v[60:63]
	v_mfma_f32_16x16x32_bf16 v[56:59], v[170:173], v[196:199], v[56:59]
	v_mfma_f32_16x16x32_bf16 v[52:55], v[162:165], v[204:207], v[52:55]
	v_mfma_f32_16x16x32_bf16 v[44:47], v[170:173], v[204:207], v[44:47]
	v_mfma_f32_16x16x32_bf16 v[36:39], v[162:165], v[212:215], v[36:39]
	v_mfma_f32_16x16x32_bf16 v[28:31], v[170:173], v[212:215], v[28:31]
	v_mfma_f32_16x16x32_bf16 v[20:23], v[162:165], v[220:223], v[20:23]
	v_mfma_f32_16x16x32_bf16 v[12:15], v[170:173], v[220:223], v[12:15]
	v_mfma_f32_16x16x32_bf16 v[48:51], v[174:177], v[192:195], v[48:51]
	v_mfma_f32_16x16x32_bf16 v[40:43], v[184:187], v[192:195], v[40:43]
	v_mfma_f32_16x16x32_bf16 v[32:35], v[174:177], v[200:203], v[32:35]
	v_mfma_f32_16x16x32_bf16 v[24:27], v[184:187], v[200:203], v[24:27]
	v_mfma_f32_16x16x32_bf16 v[16:19], v[174:177], v[208:211], v[16:19]
	v_mfma_f32_16x16x32_bf16 v[8:11], v[184:187], v[208:211], v[8:11]
	v_mfma_f32_16x16x32_bf16 v[4:7], v[174:177], v[216:219], v[4:7]
	v_mfma_f32_16x16x32_bf16 v[0:3], v[184:187], v[216:219], v[0:3]
	v_mfma_f32_16x16x32_bf16 v[48:51], v[178:181], v[196:199], v[48:51]
	v_mfma_f32_16x16x32_bf16 v[40:43], v[188:191], v[196:199], v[40:43]
	v_mfma_f32_16x16x32_bf16 v[32:35], v[178:181], v[204:207], v[32:35]
	v_mfma_f32_16x16x32_bf16 v[24:27], v[188:191], v[204:207], v[24:27]
	v_mfma_f32_16x16x32_bf16 v[16:19], v[178:181], v[212:215], v[16:19]
	v_mfma_f32_16x16x32_bf16 v[8:11], v[188:191], v[212:215], v[8:11]
	v_mfma_f32_16x16x32_bf16 v[4:7], v[178:181], v[220:223], v[4:7]
	v_mfma_f32_16x16x32_bf16 v[0:3], v[188:191], v[220:223], v[0:3]
	s_barrier
	s_add_i32 s66, 0, 0x18000
	v_add_u32_e32 v157, s66, v153
	s_add_i32 s67, 0, 0x1c000
	ds_read_b128 v[158:161], v157
	ds_read_b128 v[162:165], v157 offset:1024
	ds_read_b128 v[166:169], v157 offset:2048
	ds_read_b128 v[170:173], v157 offset:3072
	v_add_u32_e32 v157, s67, v153
	ds_read_b128 v[174:177], v157
	ds_read_b128 v[178:181], v157 offset:1024
	ds_read_b128 v[184:187], v157 offset:2048
	ds_read_b128 v[188:191], v157 offset:3072
	s_add_u32 s36, s36, 0x40000
	s_addc_u32 s37, s37, 0
	s_mov_b32 m0, s49
	v_lshl_add_u64 v[232:233], s[36:37], 0, v[128:129]
	ds_read_b128 v[192:195], v156 offset:32768
	ds_read_b128 v[196:199], v156 offset:33792
	ds_read_b128 v[200:203], v156 offset:34816
	ds_read_b128 v[204:207], v156 offset:35840
	ds_read_b128 v[208:211], v156 offset:36864
	ds_read_b128 v[212:215], v156 offset:37888
	ds_read_b128 v[216:219], v156 offset:38912
	ds_read_b128 v[220:223], v156 offset:39936
	global_load_lds_dwordx4 v[232:233], off
	v_lshl_add_u64 v[232:233], s[36:37], 0, v[132:133]
	s_mov_b32 m0, s50
	s_nop 0
	global_load_lds_dwordx4 v[232:233], off
	s_waitcnt vmcnt(8)
	s_waitcnt lgkmcnt(0)
	s_barrier
	s_waitcnt lgkmcnt(0)
	v_mfma_f32_16x16x32_bf16 v[124:127], v[158:161], v[192:195], v[124:127]
	v_mfma_f32_16x16x32_bf16 v[120:123], v[166:169], v[192:195], v[120:123]
	v_mfma_f32_16x16x32_bf16 v[116:119], v[158:161], v[200:203], v[116:119]
	v_mfma_f32_16x16x32_bf16 v[108:111], v[166:169], v[200:203], v[108:111]
	v_mfma_f32_16x16x32_bf16 v[100:103], v[158:161], v[208:211], v[100:103]
	v_mfma_f32_16x16x32_bf16 v[92:95], v[166:169], v[208:211], v[92:95]
	v_mfma_f32_16x16x32_bf16 v[84:87], v[158:161], v[216:219], v[84:87]
	v_mfma_f32_16x16x32_bf16 v[76:79], v[166:169], v[216:219], v[76:79]
	v_mfma_f32_16x16x32_bf16 v[124:127], v[162:165], v[196:199], v[124:127]
	v_mfma_f32_16x16x32_bf16 v[120:123], v[170:173], v[196:199], v[120:123]
	v_mfma_f32_16x16x32_bf16 v[116:119], v[162:165], v[204:207], v[116:119]
	v_mfma_f32_16x16x32_bf16 v[108:111], v[170:173], v[204:207], v[108:111]
	v_mfma_f32_16x16x32_bf16 v[100:103], v[162:165], v[212:215], v[100:103]
	v_mfma_f32_16x16x32_bf16 v[92:95], v[170:173], v[212:215], v[92:95]
	v_mfma_f32_16x16x32_bf16 v[84:87], v[162:165], v[220:223], v[84:87]
	v_mfma_f32_16x16x32_bf16 v[76:79], v[170:173], v[220:223], v[76:79]
	v_mfma_f32_16x16x32_bf16 v[112:115], v[174:177], v[192:195], v[112:115]
	v_mfma_f32_16x16x32_bf16 v[104:107], v[184:187], v[192:195], v[104:107]
	v_mfma_f32_16x16x32_bf16 v[96:99], v[174:177], v[200:203], v[96:99]
	v_mfma_f32_16x16x32_bf16 v[88:91], v[184:187], v[200:203], v[88:91]
	v_mfma_f32_16x16x32_bf16 v[80:83], v[174:177], v[208:211], v[80:83]
	v_mfma_f32_16x16x32_bf16 v[72:75], v[184:187], v[208:211], v[72:75]
	v_mfma_f32_16x16x32_bf16 v[68:71], v[174:177], v[216:219], v[68:71]
	v_mfma_f32_16x16x32_bf16 v[64:67], v[184:187], v[216:219], v[64:67]
	v_mfma_f32_16x16x32_bf16 v[112:115], v[178:181], v[196:199], v[112:115]
	v_mfma_f32_16x16x32_bf16 v[104:107], v[188:191], v[196:199], v[104:107]
	v_mfma_f32_16x16x32_bf16 v[96:99], v[178:181], v[204:207], v[96:99]
	v_mfma_f32_16x16x32_bf16 v[88:91], v[188:191], v[204:207], v[88:91]
	v_mfma_f32_16x16x32_bf16 v[80:83], v[178:181], v[212:215], v[80:83]
	v_mfma_f32_16x16x32_bf16 v[72:75], v[188:191], v[212:215], v[72:75]
	v_mfma_f32_16x16x32_bf16 v[68:71], v[178:181], v[220:223], v[68:71]
	v_mfma_f32_16x16x32_bf16 v[64:67], v[188:191], v[220:223], v[64:67]
	s_barrier
	s_add_i32 s36, s66, s45
	v_lshl_add_u64 v[224:225], v[224:225], 0, s[8:9]
	s_mov_b32 m0, s36
	ds_read_b128 v[192:195], v156 offset:49152
	ds_read_b128 v[196:199], v156 offset:50176
	ds_read_b128 v[200:203], v156 offset:51200
	ds_read_b128 v[204:207], v156 offset:52224
	ds_read_b128 v[208:211], v156 offset:53248
	ds_read_b128 v[212:215], v156 offset:54272
	ds_read_b128 v[216:219], v156 offset:55296
	ds_read_b128 v[220:223], v156 offset:56320
	global_load_lds_dwordx4 v[224:225], off
	s_add_i32 m0, s36, 0x2000
	s_add_u32 s34, s34, 0x40080
	v_lshl_add_u64 v[224:225], v[226:227], 0, s[8:9]
	s_addc_u32 s35, s35, 0
	s_add_i32 s36, s67, s45
	global_load_lds_dwordx4 v[224:225], off
	v_lshl_add_u64 v[224:225], s[34:35], 0, v[130:131]
	s_mov_b32 m0, s36
	s_nop 0
	global_load_lds_dwordx4 v[224:225], off
	v_lshl_add_u64 v[224:225], s[34:35], 0, v[134:135]
	s_add_i32 m0, s36, 0x2000
	s_nop 0
	global_load_lds_dwordx4 v[224:225], off
	v_lshl_add_u64 v[224:225], v[228:229], 0, s[8:9]
	s_mov_b32 m0, s51
	s_nop 0
	global_load_lds_dwordx4 v[224:225], off
	v_lshl_add_u64 v[224:225], v[230:231], 0, s[8:9]
	s_mov_b32 m0, s52
	s_nop 0
	global_load_lds_dwordx4 v[224:225], off
	s_waitcnt vmcnt(8)
	s_waitcnt lgkmcnt(0)
	s_barrier
	s_waitcnt lgkmcnt(0)
	v_mfma_f32_16x16x32_bf16 v[60:63], v[158:161], v[192:195], v[60:63]
	v_mfma_f32_16x16x32_bf16 v[56:59], v[166:169], v[192:195], v[56:59]
	v_mfma_f32_16x16x32_bf16 v[52:55], v[158:161], v[200:203], v[52:55]
	v_mfma_f32_16x16x32_bf16 v[44:47], v[166:169], v[200:203], v[44:47]
	v_mfma_f32_16x16x32_bf16 v[36:39], v[158:161], v[208:211], v[36:39]
	v_mfma_f32_16x16x32_bf16 v[28:31], v[166:169], v[208:211], v[28:31]
	v_mfma_f32_16x16x32_bf16 v[20:23], v[158:161], v[216:219], v[20:23]
	v_mfma_f32_16x16x32_bf16 v[12:15], v[166:169], v[216:219], v[12:15]
	v_mfma_f32_16x16x32_bf16 v[60:63], v[162:165], v[196:199], v[60:63]
	v_mfma_f32_16x16x32_bf16 v[56:59], v[170:173], v[196:199], v[56:59]
	v_mfma_f32_16x16x32_bf16 v[52:55], v[162:165], v[204:207], v[52:55]
	v_mfma_f32_16x16x32_bf16 v[44:47], v[170:173], v[204:207], v[44:47]
	v_mfma_f32_16x16x32_bf16 v[36:39], v[162:165], v[212:215], v[36:39]
	v_mfma_f32_16x16x32_bf16 v[28:31], v[170:173], v[212:215], v[28:31]
	v_mfma_f32_16x16x32_bf16 v[20:23], v[162:165], v[220:223], v[20:23]
	v_mfma_f32_16x16x32_bf16 v[12:15], v[170:173], v[220:223], v[12:15]
	v_mfma_f32_16x16x32_bf16 v[48:51], v[174:177], v[192:195], v[48:51]
	v_mfma_f32_16x16x32_bf16 v[40:43], v[184:187], v[192:195], v[40:43]
	v_mfma_f32_16x16x32_bf16 v[32:35], v[174:177], v[200:203], v[32:35]
	v_mfma_f32_16x16x32_bf16 v[24:27], v[184:187], v[200:203], v[24:27]
	v_mfma_f32_16x16x32_bf16 v[16:19], v[174:177], v[208:211], v[16:19]
	v_mfma_f32_16x16x32_bf16 v[8:11], v[184:187], v[208:211], v[8:11]
	v_mfma_f32_16x16x32_bf16 v[4:7], v[174:177], v[216:219], v[4:7]
	v_mfma_f32_16x16x32_bf16 v[0:3], v[184:187], v[216:219], v[0:3]
	v_mfma_f32_16x16x32_bf16 v[48:51], v[178:181], v[196:199], v[48:51]
	v_mfma_f32_16x16x32_bf16 v[40:43], v[188:191], v[196:199], v[40:43]
	v_mfma_f32_16x16x32_bf16 v[32:35], v[178:181], v[204:207], v[32:35]
	v_mfma_f32_16x16x32_bf16 v[24:27], v[188:191], v[204:207], v[24:27]
	v_mfma_f32_16x16x32_bf16 v[16:19], v[178:181], v[212:215], v[16:19]
	v_mfma_f32_16x16x32_bf16 v[8:11], v[188:191], v[212:215], v[8:11]
	v_mfma_f32_16x16x32_bf16 v[4:7], v[178:181], v[220:223], v[4:7]
	v_mfma_f32_16x16x32_bf16 v[0:3], v[188:191], v[220:223], v[0:3]
	s_barrier
	s_add_i32 s65, s65, 2
	s_add_u32 s30, s30, 0x100
	s_addc_u32 s31, s31, 0
	s_add_u32 s63, s63, 0x100
	s_addc_u32 s64, s64, 0
	s_cmp_gt_u32 s65, 13
	s_cbranch_scc0 .LBB0_1489
	s_and_b64 vcc, exec, s[10:11]
	s_cbranch_vccz .LBB0_1492
	s_barrier

.LBB0_1505:
	ds_read_b128 v[154:157], v142
	ds_read_b128 v[158:161], v142 offset:1024
	ds_read_b128 v[162:165], v142 offset:2048
	ds_read_b128 v[166:169], v142 offset:3072
	ds_read_b128 v[170:173], v143
	ds_read_b128 v[174:177], v143 offset:1024
	ds_read_b128 v[178:181], v143 offset:2048
	ds_read_b128 v[184:187], v143 offset:3072
	s_add_u32 s24, s22, 0xfffc0080
	s_addc_u32 s25, s23, -1
	s_cmp_eq_u32 s51, 12
	s_cselect_b32 s27, s15, s25
	s_cselect_b32 s26, s47, s24
	s_cselect_b32 s25, s11, s50
	s_cselect_b32 s24, s48, s49
	v_lshl_add_u64 v[150:151], s[22:23], 0, v[138:139]
	s_add_i32 m0, s35, 0xc000
	ds_read_b128 v[188:191], v146
	ds_read_b128 v[192:195], v146 offset:1024
	ds_read_b128 v[196:199], v146 offset:2048
	ds_read_b128 v[200:203], v146 offset:3072
	ds_read_b128 v[204:207], v146 offset:4096
	ds_read_b128 v[208:211], v146 offset:5120
	ds_read_b128 v[212:215], v146 offset:6144
	ds_read_b128 v[216:219], v146 offset:7168
	global_load_lds_dwordx4 v[150:151], off
	v_lshl_add_u64 v[150:151], s[22:23], 0, v[140:141]
	s_add_i32 m0, s35, 0xe000
	s_nop 0
	global_load_lds_dwordx4 v[150:151], off
	s_waitcnt vmcnt(8)
	s_waitcnt lgkmcnt(0)
	s_barrier
	s_waitcnt lgkmcnt(0)
	v_mfma_f32_16x16x32_bf16 v[124:127], v[154:157], v[188:191], v[124:127]
	v_mfma_f32_16x16x32_bf16 v[120:123], v[162:165], v[188:191], v[120:123]
	v_mfma_f32_16x16x32_bf16 v[116:119], v[154:157], v[196:199], v[116:119]
	v_mfma_f32_16x16x32_bf16 v[108:111], v[162:165], v[196:199], v[108:111]
	v_mfma_f32_16x16x32_bf16 v[100:103], v[154:157], v[204:207], v[100:103]
	v_mfma_f32_16x16x32_bf16 v[92:95], v[162:165], v[204:207], v[92:95]
	v_mfma_f32_16x16x32_bf16 v[84:87], v[154:157], v[212:215], v[84:87]
	v_mfma_f32_16x16x32_bf16 v[76:79], v[162:165], v[212:215], v[76:79]
	v_mfma_f32_16x16x32_bf16 v[124:127], v[158:161], v[192:195], v[124:127]
	v_mfma_f32_16x16x32_bf16 v[120:123], v[166:169], v[192:195], v[120:123]
	v_mfma_f32_16x16x32_bf16 v[116:119], v[158:161], v[200:203], v[116:119]
	v_mfma_f32_16x16x32_bf16 v[108:111], v[166:169], v[200:203], v[108:111]
	v_mfma_f32_16x16x32_bf16 v[100:103], v[158:161], v[208:211], v[100:103]
	v_mfma_f32_16x16x32_bf16 v[92:95], v[166:169], v[208:211], v[92:95]
	v_mfma_f32_16x16x32_bf16 v[84:87], v[158:161], v[216:219], v[84:87]
	v_mfma_f32_16x16x32_bf16 v[76:79], v[166:169], v[216:219], v[76:79]
	v_mfma_f32_16x16x32_bf16 v[112:115], v[170:173], v[188:191], v[112:115]
	v_mfma_f32_16x16x32_bf16 v[104:107], v[178:181], v[188:191], v[104:107]
	v_mfma_f32_16x16x32_bf16 v[96:99], v[170:173], v[196:199], v[96:99]
	v_mfma_f32_16x16x32_bf16 v[88:91], v[178:181], v[196:199], v[88:91]
	v_mfma_f32_16x16x32_bf16 v[80:83], v[170:173], v[204:207], v[80:83]
	v_mfma_f32_16x16x32_bf16 v[72:75], v[178:181], v[204:207], v[72:75]
	v_mfma_f32_16x16x32_bf16 v[68:71], v[170:173], v[212:215], v[68:71]
	v_mfma_f32_16x16x32_bf16 v[64:67], v[178:181], v[212:215], v[64:67]
	v_mfma_f32_16x16x32_bf16 v[112:115], v[174:177], v[192:195], v[112:115]
	v_mfma_f32_16x16x32_bf16 v[104:107], v[184:187], v[192:195], v[104:107]
	v_mfma_f32_16x16x32_bf16 v[96:99], v[174:177], v[200:203], v[96:99]
	v_mfma_f32_16x16x32_bf16 v[88:91], v[184:187], v[200:203], v[88:91]
	v_mfma_f32_16x16x32_bf16 v[80:83], v[174:177], v[208:211], v[80:83]
	v_mfma_f32_16x16x32_bf16 v[72:75], v[184:187], v[208:211], v[72:75]
	v_mfma_f32_16x16x32_bf16 v[68:71], v[174:177], v[216:219], v[68:71]
	v_mfma_f32_16x16x32_bf16 v[64:67], v[184:187], v[216:219], v[64:67]
	s_barrier
	s_add_i32 s52, s44, s31
	v_lshl_add_u64 v[150:151], s[24:25], 0, v[130:131]
	s_mov_b32 m0, s52
	ds_read_b128 v[188:191], v146 offset:16384
	ds_read_b128 v[192:195], v146 offset:17408
	ds_read_b128 v[196:199], v146 offset:18432
	ds_read_b128 v[200:203], v146 offset:19456
	ds_read_b128 v[204:207], v146 offset:20480
	ds_read_b128 v[208:211], v146 offset:21504
	ds_read_b128 v[212:215], v146 offset:22528
	ds_read_b128 v[216:219], v146 offset:23552
	global_load_lds_dwordx4 v[150:151], off
	s_add_i32 m0, s52, 0x2000
	s_add_u32 s52, s24, 0x40000
	v_lshl_add_u64 v[220:221], s[24:25], 0, v[134:135]
	s_addc_u32 s53, s25, 0
	s_add_i32 s54, s45, s31
	global_load_lds_dwordx4 v[220:221], off
	v_lshl_add_u64 v[222:223], s[52:53], 0, v[130:131]
	s_mov_b32 m0, s54
	v_lshl_add_u64 v[224:225], s[26:27], 0, v[132:133]
	global_load_lds_dwordx4 v[222:223], off
	v_lshl_add_u64 v[222:223], s[52:53], 0, v[134:135]
	s_add_i32 m0, s54, 0x2000
	s_nop 0
	global_load_lds_dwordx4 v[222:223], off
	v_lshl_add_u64 v[222:223], s[26:27], 0, v[128:129]
	s_mov_b32 m0, s35
	s_nop 0
	global_load_lds_dwordx4 v[222:223], off
	s_mov_b32 m0, s36
	s_nop 0
	global_load_lds_dwordx4 v[224:225], off
	s_waitcnt vmcnt(8)
	s_waitcnt lgkmcnt(0)
	s_barrier
	s_waitcnt lgkmcnt(0)
	v_mfma_f32_16x16x32_bf16 v[60:63], v[154:157], v[188:191], v[60:63]
	v_mfma_f32_16x16x32_bf16 v[56:59], v[162:165], v[188:191], v[56:59]
	v_mfma_f32_16x16x32_bf16 v[52:55], v[154:157], v[196:199], v[52:55]
	v_mfma_f32_16x16x32_bf16 v[44:47], v[162:165], v[196:199], v[44:47]
	v_mfma_f32_16x16x32_bf16 v[36:39], v[154:157], v[204:207], v[36:39]
	v_mfma_f32_16x16x32_bf16 v[28:31], v[162:165], v[204:207], v[28:31]
	v_mfma_f32_16x16x32_bf16 v[20:23], v[154:157], v[212:215], v[20:23]
	v_mfma_f32_16x16x32_bf16 v[12:15], v[162:165], v[212:215], v[12:15]
	v_mfma_f32_16x16x32_bf16 v[60:63], v[158:161], v[192:195], v[60:63]
	v_mfma_f32_16x16x32_bf16 v[56:59], v[166:169], v[192:195], v[56:59]
	v_mfma_f32_16x16x32_bf16 v[52:55], v[158:161], v[200:203], v[52:55]
	v_mfma_f32_16x16x32_bf16 v[44:47], v[166:169], v[200:203], v[44:47]
	v_mfma_f32_16x16x32_bf16 v[36:39], v[158:161], v[208:211], v[36:39]
	v_mfma_f32_16x16x32_bf16 v[28:31], v[166:169], v[208:211], v[28:31]
	v_mfma_f32_16x16x32_bf16 v[20:23], v[158:161], v[216:219], v[20:23]
	v_mfma_f32_16x16x32_bf16 v[12:15], v[166:169], v[216:219], v[12:15]
	v_mfma_f32_16x16x32_bf16 v[48:51], v[170:173], v[188:191], v[48:51]
	v_mfma_f32_16x16x32_bf16 v[40:43], v[178:181], v[188:191], v[40:43]
	v_mfma_f32_16x16x32_bf16 v[32:35], v[170:173], v[196:199], v[32:35]
	v_mfma_f32_16x16x32_bf16 v[24:27], v[178:181], v[196:199], v[24:27]
	v_mfma_f32_16x16x32_bf16 v[16:19], v[170:173], v[204:207], v[16:19]
	v_mfma_f32_16x16x32_bf16 v[8:11], v[178:181], v[204:207], v[8:11]
	v_mfma_f32_16x16x32_bf16 v[4:7], v[170:173], v[212:215], v[4:7]
	v_mfma_f32_16x16x32_bf16 v[0:3], v[178:181], v[212:215], v[0:3]
	v_mfma_f32_16x16x32_bf16 v[48:51], v[174:177], v[192:195], v[48:51]
	v_mfma_f32_16x16x32_bf16 v[40:43], v[184:187], v[192:195], v[40:43]
	v_mfma_f32_16x16x32_bf16 v[32:35], v[174:177], v[200:203], v[32:35]
	v_mfma_f32_16x16x32_bf16 v[24:27], v[184:187], v[200:203], v[24:27]
	v_mfma_f32_16x16x32_bf16 v[16:19], v[174:177], v[208:211], v[16:19]
	v_mfma_f32_16x16x32_bf16 v[8:11], v[184:187], v[208:211], v[8:11]
	v_mfma_f32_16x16x32_bf16 v[4:7], v[174:177], v[216:219], v[4:7]
	v_mfma_f32_16x16x32_bf16 v[0:3], v[184:187], v[216:219], v[0:3]
	s_barrier
	s_add_i32 s52, 0, 0x18000
	v_add_u32_e32 v147, s52, v149
	s_add_i32 s53, 0, 0x1c000
	ds_read_b128 v[154:157], v147
	ds_read_b128 v[158:161], v147 offset:1024
	ds_read_b128 v[162:165], v147 offset:2048
	ds_read_b128 v[166:169], v147 offset:3072
	v_add_u32_e32 v147, s53, v149
	ds_read_b128 v[170:173], v147
	ds_read_b128 v[174:177], v147 offset:1024
	ds_read_b128 v[178:181], v147 offset:2048
	ds_read_b128 v[184:187], v147 offset:3072
	s_add_u32 s26, s26, 0x40000
	s_addc_u32 s27, s27, 0
	s_mov_b32 m0, s37
	v_lshl_add_u64 v[226:227], s[26:27], 0, v[128:129]
	ds_read_b128 v[188:191], v146 offset:32768
	ds_read_b128 v[192:195], v146 offset:33792
	ds_read_b128 v[196:199], v146 offset:34816
	ds_read_b128 v[200:203], v146 offset:35840
	ds_read_b128 v[204:207], v146 offset:36864
	ds_read_b128 v[208:211], v146 offset:37888
	ds_read_b128 v[212:215], v146 offset:38912
	ds_read_b128 v[216:219], v146 offset:39936
	global_load_lds_dwordx4 v[226:227], off
	v_lshl_add_u64 v[226:227], s[26:27], 0, v[132:133]
	s_mov_b32 m0, s39
	s_nop 0
	global_load_lds_dwordx4 v[226:227], off
	s_waitcnt vmcnt(8)
	s_waitcnt lgkmcnt(0)
	s_barrier
	s_waitcnt lgkmcnt(0)
	v_mfma_f32_16x16x32_bf16 v[124:127], v[154:157], v[188:191], v[124:127]
	v_mfma_f32_16x16x32_bf16 v[120:123], v[162:165], v[188:191], v[120:123]
	v_mfma_f32_16x16x32_bf16 v[116:119], v[154:157], v[196:199], v[116:119]
	v_mfma_f32_16x16x32_bf16 v[108:111], v[162:165], v[196:199], v[108:111]
	v_mfma_f32_16x16x32_bf16 v[100:103], v[154:157], v[204:207], v[100:103]
	v_mfma_f32_16x16x32_bf16 v[92:95], v[162:165], v[204:207], v[92:95]
	v_mfma_f32_16x16x32_bf16 v[84:87], v[154:157], v[212:215], v[84:87]
	v_mfma_f32_16x16x32_bf16 v[76:79], v[162:165], v[212:215], v[76:79]
	v_mfma_f32_16x16x32_bf16 v[124:127], v[158:161], v[192:195], v[124:127]
	v_mfma_f32_16x16x32_bf16 v[120:123], v[166:169], v[192:195], v[120:123]
	v_mfma_f32_16x16x32_bf16 v[116:119], v[158:161], v[200:203], v[116:119]
	v_mfma_f32_16x16x32_bf16 v[108:111], v[166:169], v[200:203], v[108:111]
	v_mfma_f32_16x16x32_bf16 v[100:103], v[158:161], v[208:211], v[100:103]
	v_mfma_f32_16x16x32_bf16 v[92:95], v[166:169], v[208:211], v[92:95]
	v_mfma_f32_16x16x32_bf16 v[84:87], v[158:161], v[216:219], v[84:87]
	v_mfma_f32_16x16x32_bf16 v[76:79], v[166:169], v[216:219], v[76:79]
	v_mfma_f32_16x16x32_bf16 v[112:115], v[170:173], v[188:191], v[112:115]
	v_mfma_f32_16x16x32_bf16 v[104:107], v[178:181], v[188:191], v[104:107]
	v_mfma_f32_16x16x32_bf16 v[96:99], v[170:173], v[196:199], v[96:99]
	v_mfma_f32_16x16x32_bf16 v[88:91], v[178:181], v[196:199], v[88:91]
	v_mfma_f32_16x16x32_bf16 v[80:83], v[170:173], v[204:207], v[80:83]
	v_mfma_f32_16x16x32_bf16 v[72:75], v[178:181], v[204:207], v[72:75]
	v_mfma_f32_16x16x32_bf16 v[68:71], v[170:173], v[212:215], v[68:71]
	v_mfma_f32_16x16x32_bf16 v[64:67], v[178:181], v[212:215], v[64:67]
	v_mfma_f32_16x16x32_bf16 v[112:115], v[174:177], v[192:195], v[112:115]
	v_mfma_f32_16x16x32_bf16 v[104:107], v[184:187], v[192:195], v[104:107]
	v_mfma_f32_16x16x32_bf16 v[96:99], v[174:177], v[200:203], v[96:99]
	v_mfma_f32_16x16x32_bf16 v[88:91], v[184:187], v[200:203], v[88:91]
	v_mfma_f32_16x16x32_bf16 v[80:83], v[174:177], v[208:211], v[80:83]
	v_mfma_f32_16x16x32_bf16 v[72:75], v[184:187], v[208:211], v[72:75]
	v_mfma_f32_16x16x32_bf16 v[68:71], v[174:177], v[216:219], v[68:71]
	v_mfma_f32_16x16x32_bf16 v[64:67], v[184:187], v[216:219], v[64:67]
	s_barrier
	s_add_i32 s26, s52, s31
	v_lshl_add_u64 v[150:151], v[150:151], 0, s[6:7]
	s_mov_b32 m0, s26
	ds_read_b128 v[188:191], v146 offset:49152
	ds_read_b128 v[192:195], v146 offset:50176
	ds_read_b128 v[196:199], v146 offset:51200
	ds_read_b128 v[200:203], v146 offset:52224
	ds_read_b128 v[204:207], v146 offset:53248
	ds_read_b128 v[208:211], v146 offset:54272
	ds_read_b128 v[212:215], v146 offset:55296
	ds_read_b128 v[216:219], v146 offset:56320
	global_load_lds_dwordx4 v[150:151], off
	s_add_i32 m0, s26, 0x2000
	s_add_u32 s24, s24, 0x40080
	v_lshl_add_u64 v[150:151], v[220:221], 0, s[6:7]
	s_addc_u32 s25, s25, 0
	s_add_i32 s26, s53, s31
	global_load_lds_dwordx4 v[150:151], off
	v_lshl_add_u64 v[150:151], s[24:25], 0, v[130:131]
	s_mov_b32 m0, s26
	s_nop 0
	global_load_lds_dwordx4 v[150:151], off
	v_lshl_add_u64 v[150:151], s[24:25], 0, v[134:135]
	s_add_i32 m0, s26, 0x2000
	s_nop 0
	global_load_lds_dwordx4 v[150:151], off
	v_lshl_add_u64 v[150:151], v[222:223], 0, s[6:7]
	s_mov_b32 m0, s41
	s_nop 0
	global_load_lds_dwordx4 v[150:151], off
	v_lshl_add_u64 v[150:151], v[224:225], 0, s[6:7]
	s_mov_b32 m0, s42
	s_nop 0
	global_load_lds_dwordx4 v[150:151], off
	s_waitcnt vmcnt(8)
	s_waitcnt lgkmcnt(0)
	s_barrier
	s_waitcnt lgkmcnt(0)
	v_mfma_f32_16x16x32_bf16 v[60:63], v[154:157], v[188:191], v[60:63]
	v_mfma_f32_16x16x32_bf16 v[56:59], v[162:165], v[188:191], v[56:59]
	v_mfma_f32_16x16x32_bf16 v[52:55], v[154:157], v[196:199], v[52:55]
	v_mfma_f32_16x16x32_bf16 v[44:47], v[162:165], v[196:199], v[44:47]
	v_mfma_f32_16x16x32_bf16 v[36:39], v[154:157], v[204:207], v[36:39]
	v_mfma_f32_16x16x32_bf16 v[28:31], v[162:165], v[204:207], v[28:31]
	v_mfma_f32_16x16x32_bf16 v[20:23], v[154:157], v[212:215], v[20:23]
	v_mfma_f32_16x16x32_bf16 v[12:15], v[162:165], v[212:215], v[12:15]
	v_mfma_f32_16x16x32_bf16 v[60:63], v[158:161], v[192:195], v[60:63]
	v_mfma_f32_16x16x32_bf16 v[56:59], v[166:169], v[192:195], v[56:59]
	v_mfma_f32_16x16x32_bf16 v[52:55], v[158:161], v[200:203], v[52:55]
	v_mfma_f32_16x16x32_bf16 v[44:47], v[166:169], v[200:203], v[44:47]
	v_mfma_f32_16x16x32_bf16 v[36:39], v[158:161], v[208:211], v[36:39]
	v_mfma_f32_16x16x32_bf16 v[28:31], v[166:169], v[208:211], v[28:31]
	v_mfma_f32_16x16x32_bf16 v[20:23], v[158:161], v[216:219], v[20:23]
	v_mfma_f32_16x16x32_bf16 v[12:15], v[166:169], v[216:219], v[12:15]
	v_mfma_f32_16x16x32_bf16 v[48:51], v[170:173], v[188:191], v[48:51]
	v_mfma_f32_16x16x32_bf16 v[40:43], v[178:181], v[188:191], v[40:43]
	v_mfma_f32_16x16x32_bf16 v[32:35], v[170:173], v[196:199], v[32:35]
	v_mfma_f32_16x16x32_bf16 v[24:27], v[178:181], v[196:199], v[24:27]
	v_mfma_f32_16x16x32_bf16 v[16:19], v[170:173], v[204:207], v[16:19]
	v_mfma_f32_16x16x32_bf16 v[8:11], v[178:181], v[204:207], v[8:11]
	v_mfma_f32_16x16x32_bf16 v[4:7], v[170:173], v[212:215], v[4:7]
	v_mfma_f32_16x16x32_bf16 v[0:3], v[178:181], v[212:215], v[0:3]
	v_mfma_f32_16x16x32_bf16 v[48:51], v[174:177], v[192:195], v[48:51]
	v_mfma_f32_16x16x32_bf16 v[40:43], v[184:187], v[192:195], v[40:43]
	v_mfma_f32_16x16x32_bf16 v[32:35], v[174:177], v[200:203], v[32:35]
	v_mfma_f32_16x16x32_bf16 v[24:27], v[184:187], v[200:203], v[24:27]
	v_mfma_f32_16x16x32_bf16 v[16:19], v[174:177], v[208:211], v[16:19]
	v_mfma_f32_16x16x32_bf16 v[8:11], v[184:187], v[208:211], v[8:11]
	v_mfma_f32_16x16x32_bf16 v[4:7], v[174:177], v[216:219], v[4:7]
	v_mfma_f32_16x16x32_bf16 v[0:3], v[184:187], v[216:219], v[0:3]
	s_barrier
	s_add_i32 s51, s51, 2
	s_add_u32 s22, s22, 0x100
	s_addc_u32 s23, s23, 0
	s_add_u32 s49, s49, 0x100
	s_addc_u32 s50, s50, 0
	s_cmp_gt_u32 s51, 13
	s_cbranch_scc0 .LBB0_1505
	s_and_b64 vcc, exec, s[8:9]
	s_cbranch_vccz .LBB0_1508
	s_barrier

.Lp7_skip_rescale:
	ds_read_b128 v[128:131], v184
	ds_read_b128 v[132:135], v184 offset:1024
	ds_read_b128 v[136:139], v184 offset:2048
	ds_read_b128 v[140:143], v184 offset:3072
	ds_read_b128 v[166:169], v185
	ds_read_b128 v[170:173], v185 offset:1024
	ds_read_b128 v[174:177], v185 offset:2048
	ds_read_b128 v[188:191], v185 offset:3072
	s_add_u32 s34, s30, 0xfffc0080
	s_addc_u32 s35, s31, -1
	s_cmp_eq_u32 s56, 12
	s_cselect_b32 s37, s21, s35
	s_cselect_b32 s36, s27, s34
	s_cselect_b32 s35, s19, s55
	s_cselect_b32 s34, s29, s54
	v_lshl_add_u64 v[178:179], s[30:31], 0, v[158:159]
	s_add_i32 m0, s42, 0xc000
	ds_read_b128 v[192:195], v186
	ds_read_b128 v[196:199], v186 offset:1024
	ds_read_b128 v[200:203], v186 offset:2048
	ds_read_b128 v[204:207], v186 offset:3072
	ds_read_b128 v[208:211], v186 offset:4096
	ds_read_b128 v[212:215], v186 offset:5120
	ds_read_b128 v[216:219], v186 offset:6144
	ds_read_b128 v[220:223], v186 offset:7168
	global_load_lds_dwordx4 v[178:179], off
	v_lshl_add_u64 v[178:179], s[30:31], 0, v[160:161]
	s_add_i32 m0, s42, 0xe000
	s_nop 0
	global_load_lds_dwordx4 v[178:179], off
	s_waitcnt vmcnt(8)
	s_waitcnt lgkmcnt(0)
	s_barrier
	s_waitcnt lgkmcnt(0)
	v_mfma_f32_16x16x32_bf16 v[124:127], v[128:131], v[192:195], v[124:127]
	v_mfma_f32_16x16x32_bf16 v[120:123], v[136:139], v[192:195], v[120:123]
	v_mfma_f32_16x16x32_bf16 v[108:111], v[128:131], v[200:203], v[108:111]
	v_mfma_f32_16x16x32_bf16 v[104:107], v[136:139], v[200:203], v[104:107]
	v_mfma_f32_16x16x32_bf16 v[92:95], v[128:131], v[208:211], v[92:95]
	v_mfma_f32_16x16x32_bf16 v[88:91], v[136:139], v[208:211], v[88:91]
	v_mfma_f32_16x16x32_bf16 v[76:79], v[128:131], v[216:219], v[76:79]
	v_mfma_f32_16x16x32_bf16 v[72:75], v[136:139], v[216:219], v[72:75]
	v_mfma_f32_16x16x32_bf16 v[124:127], v[132:135], v[196:199], v[124:127]
	v_mfma_f32_16x16x32_bf16 v[120:123], v[140:143], v[196:199], v[120:123]
	v_mfma_f32_16x16x32_bf16 v[108:111], v[132:135], v[204:207], v[108:111]
	v_mfma_f32_16x16x32_bf16 v[104:107], v[140:143], v[204:207], v[104:107]
	v_mfma_f32_16x16x32_bf16 v[92:95], v[132:135], v[212:215], v[92:95]
	v_mfma_f32_16x16x32_bf16 v[88:91], v[140:143], v[212:215], v[88:91]
	v_mfma_f32_16x16x32_bf16 v[76:79], v[132:135], v[220:223], v[76:79]
	v_mfma_f32_16x16x32_bf16 v[72:75], v[140:143], v[220:223], v[72:75]
	v_mfma_f32_16x16x32_bf16 v[116:119], v[166:169], v[192:195], v[116:119]
	v_mfma_f32_16x16x32_bf16 v[112:115], v[174:177], v[192:195], v[112:115]
	v_mfma_f32_16x16x32_bf16 v[100:103], v[166:169], v[200:203], v[100:103]
	v_mfma_f32_16x16x32_bf16 v[96:99], v[174:177], v[200:203], v[96:99]
	v_mfma_f32_16x16x32_bf16 v[84:87], v[166:169], v[208:211], v[84:87]
	v_mfma_f32_16x16x32_bf16 v[80:83], v[174:177], v[208:211], v[80:83]
	v_mfma_f32_16x16x32_bf16 v[68:71], v[166:169], v[216:219], v[68:71]
	v_mfma_f32_16x16x32_bf16 v[64:67], v[174:177], v[216:219], v[64:67]
	v_mfma_f32_16x16x32_bf16 v[116:119], v[170:173], v[196:199], v[116:119]
	v_mfma_f32_16x16x32_bf16 v[112:115], v[188:191], v[196:199], v[112:115]
	v_mfma_f32_16x16x32_bf16 v[100:103], v[170:173], v[204:207], v[100:103]
	v_mfma_f32_16x16x32_bf16 v[96:99], v[188:191], v[204:207], v[96:99]
	v_mfma_f32_16x16x32_bf16 v[84:87], v[170:173], v[212:215], v[84:87]
	v_mfma_f32_16x16x32_bf16 v[80:83], v[188:191], v[212:215], v[80:83]
	v_mfma_f32_16x16x32_bf16 v[68:71], v[170:173], v[220:223], v[68:71]
	v_mfma_f32_16x16x32_bf16 v[64:67], v[188:191], v[220:223], v[64:67]
	s_barrier
	s_add_i32 s57, s52, s41
	v_lshl_add_u64 v[178:179], s[34:35], 0, v[148:149]
	s_mov_b32 m0, s57
	ds_read_b128 v[192:195], v186 offset:16384
	ds_read_b128 v[196:199], v186 offset:17408
	ds_read_b128 v[200:203], v186 offset:18432
	ds_read_b128 v[204:207], v186 offset:19456
	ds_read_b128 v[208:211], v186 offset:20480
	ds_read_b128 v[212:215], v186 offset:21504
	ds_read_b128 v[216:219], v186 offset:22528
	ds_read_b128 v[220:223], v186 offset:23552
	global_load_lds_dwordx4 v[178:179], off
	s_add_i32 m0, s57, 0x2000
	s_add_u32 s58, s34, 0x40000
	v_lshl_add_u64 v[224:225], s[34:35], 0, v[152:153]
	s_addc_u32 s59, s35, 0
	s_add_i32 s57, s53, s41
	global_load_lds_dwordx4 v[224:225], off
	v_lshl_add_u64 v[226:227], s[58:59], 0, v[148:149]
	s_mov_b32 m0, s57
	v_lshl_add_u64 v[228:229], s[36:37], 0, v[150:151]
	global_load_lds_dwordx4 v[226:227], off
	v_lshl_add_u64 v[226:227], s[58:59], 0, v[152:153]
	s_add_i32 m0, s57, 0x2000
	s_nop 0
	global_load_lds_dwordx4 v[226:227], off
	v_lshl_add_u64 v[226:227], s[36:37], 0, v[146:147]
	s_mov_b32 m0, s42
	s_nop 0
	global_load_lds_dwordx4 v[226:227], off
	s_mov_b32 m0, s43
	s_nop 0
	global_load_lds_dwordx4 v[228:229], off
	s_waitcnt vmcnt(8)
	s_waitcnt lgkmcnt(0)
	s_barrier
	s_waitcnt lgkmcnt(0)
	v_mfma_f32_16x16x32_bf16 v[60:63], v[128:131], v[192:195], v[60:63]
	v_mfma_f32_16x16x32_bf16 v[56:59], v[136:139], v[192:195], v[56:59]
	v_mfma_f32_16x16x32_bf16 v[44:47], v[128:131], v[200:203], v[44:47]
	v_mfma_f32_16x16x32_bf16 v[40:43], v[136:139], v[200:203], v[40:43]
	v_mfma_f32_16x16x32_bf16 v[28:31], v[128:131], v[208:211], v[28:31]
	v_mfma_f32_16x16x32_bf16 v[24:27], v[136:139], v[208:211], v[24:27]
	v_mfma_f32_16x16x32_bf16 v[12:15], v[128:131], v[216:219], v[12:15]
	v_mfma_f32_16x16x32_bf16 v[8:11], v[136:139], v[216:219], v[8:11]
	v_mfma_f32_16x16x32_bf16 v[60:63], v[132:135], v[196:199], v[60:63]
	v_mfma_f32_16x16x32_bf16 v[56:59], v[140:143], v[196:199], v[56:59]
	v_mfma_f32_16x16x32_bf16 v[44:47], v[132:135], v[204:207], v[44:47]
	v_mfma_f32_16x16x32_bf16 v[40:43], v[140:143], v[204:207], v[40:43]
	v_mfma_f32_16x16x32_bf16 v[28:31], v[132:135], v[212:215], v[28:31]
	v_mfma_f32_16x16x32_bf16 v[24:27], v[140:143], v[212:215], v[24:27]
	v_mfma_f32_16x16x32_bf16 v[12:15], v[132:135], v[220:223], v[12:15]
	v_mfma_f32_16x16x32_bf16 v[8:11], v[140:143], v[220:223], v[8:11]
	v_mfma_f32_16x16x32_bf16 v[52:55], v[166:169], v[192:195], v[52:55]
	v_mfma_f32_16x16x32_bf16 v[48:51], v[174:177], v[192:195], v[48:51]
	v_mfma_f32_16x16x32_bf16 v[36:39], v[166:169], v[200:203], v[36:39]
	v_mfma_f32_16x16x32_bf16 v[32:35], v[174:177], v[200:203], v[32:35]
	v_mfma_f32_16x16x32_bf16 v[20:23], v[166:169], v[208:211], v[20:23]
	v_mfma_f32_16x16x32_bf16 v[16:19], v[174:177], v[208:211], v[16:19]
	v_mfma_f32_16x16x32_bf16 v[4:7], v[166:169], v[216:219], v[4:7]
	v_mfma_f32_16x16x32_bf16 v[0:3], v[174:177], v[216:219], v[0:3]
	v_mfma_f32_16x16x32_bf16 v[52:55], v[170:173], v[196:199], v[52:55]
	v_mfma_f32_16x16x32_bf16 v[48:51], v[188:191], v[196:199], v[48:51]
	v_mfma_f32_16x16x32_bf16 v[36:39], v[170:173], v[204:207], v[36:39]
	v_mfma_f32_16x16x32_bf16 v[32:35], v[188:191], v[204:207], v[32:35]
	v_mfma_f32_16x16x32_bf16 v[20:23], v[170:173], v[212:215], v[20:23]
	v_mfma_f32_16x16x32_bf16 v[16:19], v[188:191], v[212:215], v[16:19]
	v_mfma_f32_16x16x32_bf16 v[4:7], v[170:173], v[220:223], v[4:7]
	v_mfma_f32_16x16x32_bf16 v[0:3], v[188:191], v[220:223], v[0:3]
	s_barrier
	s_add_i32 s57, 0, 0x18000
	s_add_i32 s58, 0, 0x1c000
	v_add_u32_e32 v140, s57, v183
	v_add_u32_e32 v188, s58, v183
	ds_read_b128 v[128:131], v140
	ds_read_b128 v[132:135], v140 offset:1024
	ds_read_b128 v[136:139], v140 offset:2048
	ds_read_b128 v[140:143], v140 offset:3072
	ds_read_b128 v[166:169], v188
	ds_read_b128 v[170:173], v188 offset:1024
	ds_read_b128 v[174:177], v188 offset:2048
	ds_read_b128 v[188:191], v188 offset:3072
	s_add_u32 s36, s36, 0x40000
	s_addc_u32 s37, s37, 0
	s_mov_b32 m0, s44
	v_lshl_add_u64 v[230:231], s[36:37], 0, v[146:147]
	ds_read_b128 v[192:195], v186 offset:32768
	ds_read_b128 v[196:199], v186 offset:33792
	ds_read_b128 v[200:203], v186 offset:34816
	ds_read_b128 v[204:207], v186 offset:35840
	ds_read_b128 v[208:211], v186 offset:36864
	ds_read_b128 v[212:215], v186 offset:37888
	ds_read_b128 v[216:219], v186 offset:38912
	ds_read_b128 v[220:223], v186 offset:39936
	global_load_lds_dwordx4 v[230:231], off
	v_lshl_add_u64 v[230:231], s[36:37], 0, v[150:151]
	s_mov_b32 m0, s45
	s_nop 0
	global_load_lds_dwordx4 v[230:231], off
	s_waitcnt vmcnt(8)
	s_waitcnt lgkmcnt(0)
	s_barrier
	s_waitcnt lgkmcnt(0)
	v_mfma_f32_16x16x32_bf16 v[124:127], v[128:131], v[192:195], v[124:127]
	v_mfma_f32_16x16x32_bf16 v[120:123], v[136:139], v[192:195], v[120:123]
	v_mfma_f32_16x16x32_bf16 v[108:111], v[128:131], v[200:203], v[108:111]
	v_mfma_f32_16x16x32_bf16 v[104:107], v[136:139], v[200:203], v[104:107]
	v_mfma_f32_16x16x32_bf16 v[92:95], v[128:131], v[208:211], v[92:95]
	v_mfma_f32_16x16x32_bf16 v[88:91], v[136:139], v[208:211], v[88:91]
	v_mfma_f32_16x16x32_bf16 v[76:79], v[128:131], v[216:219], v[76:79]
	v_mfma_f32_16x16x32_bf16 v[72:75], v[136:139], v[216:219], v[72:75]
	v_mfma_f32_16x16x32_bf16 v[124:127], v[132:135], v[196:199], v[124:127]
	v_mfma_f32_16x16x32_bf16 v[120:123], v[140:143], v[196:199], v[120:123]
	v_mfma_f32_16x16x32_bf16 v[108:111], v[132:135], v[204:207], v[108:111]
	v_mfma_f32_16x16x32_bf16 v[104:107], v[140:143], v[204:207], v[104:107]
	v_mfma_f32_16x16x32_bf16 v[92:95], v[132:135], v[212:215], v[92:95]
	v_mfma_f32_16x16x32_bf16 v[88:91], v[140:143], v[212:215], v[88:91]
	v_mfma_f32_16x16x32_bf16 v[76:79], v[132:135], v[220:223], v[76:79]
	v_mfma_f32_16x16x32_bf16 v[72:75], v[140:143], v[220:223], v[72:75]
	v_mfma_f32_16x16x32_bf16 v[116:119], v[166:169], v[192:195], v[116:119]
	v_mfma_f32_16x16x32_bf16 v[112:115], v[174:177], v[192:195], v[112:115]
	v_mfma_f32_16x16x32_bf16 v[100:103], v[166:169], v[200:203], v[100:103]
	v_mfma_f32_16x16x32_bf16 v[96:99], v[174:177], v[200:203], v[96:99]
	v_mfma_f32_16x16x32_bf16 v[84:87], v[166:169], v[208:211], v[84:87]
	v_mfma_f32_16x16x32_bf16 v[80:83], v[174:177], v[208:211], v[80:83]
	v_mfma_f32_16x16x32_bf16 v[68:71], v[166:169], v[216:219], v[68:71]
	v_mfma_f32_16x16x32_bf16 v[64:67], v[174:177], v[216:219], v[64:67]
	v_mfma_f32_16x16x32_bf16 v[116:119], v[170:173], v[196:199], v[116:119]
	v_mfma_f32_16x16x32_bf16 v[112:115], v[188:191], v[196:199], v[112:115]
	v_mfma_f32_16x16x32_bf16 v[100:103], v[170:173], v[204:207], v[100:103]
	v_mfma_f32_16x16x32_bf16 v[96:99], v[188:191], v[204:207], v[96:99]
	v_mfma_f32_16x16x32_bf16 v[84:87], v[170:173], v[212:215], v[84:87]
	v_mfma_f32_16x16x32_bf16 v[80:83], v[188:191], v[212:215], v[80:83]
	v_mfma_f32_16x16x32_bf16 v[68:71], v[170:173], v[220:223], v[68:71]
	v_mfma_f32_16x16x32_bf16 v[64:67], v[188:191], v[220:223], v[64:67]
	s_barrier
	s_add_i32 s36, s57, s41
	v_lshl_add_u64 v[178:179], v[178:179], 0, s[12:13]
	s_mov_b32 m0, s36
	ds_read_b128 v[192:195], v186 offset:49152
	ds_read_b128 v[196:199], v186 offset:50176
	ds_read_b128 v[200:203], v186 offset:51200
	ds_read_b128 v[204:207], v186 offset:52224
	ds_read_b128 v[208:211], v186 offset:53248
	ds_read_b128 v[212:215], v186 offset:54272
	ds_read_b128 v[216:219], v186 offset:55296
	ds_read_b128 v[220:223], v186 offset:56320
	global_load_lds_dwordx4 v[178:179], off
	s_add_i32 m0, s36, 0x2000
	s_add_u32 s34, s34, 0x40080
	v_lshl_add_u64 v[178:179], v[224:225], 0, s[12:13]
	s_addc_u32 s35, s35, 0
	s_add_i32 s36, s58, s41
	global_load_lds_dwordx4 v[178:179], off
	v_lshl_add_u64 v[178:179], s[34:35], 0, v[148:149]
	s_mov_b32 m0, s36
	s_nop 0
	global_load_lds_dwordx4 v[178:179], off
	v_lshl_add_u64 v[178:179], s[34:35], 0, v[152:153]
	s_add_i32 m0, s36, 0x2000
	s_nop 0
	global_load_lds_dwordx4 v[178:179], off
	v_lshl_add_u64 v[178:179], v[226:227], 0, s[12:13]
	s_mov_b32 m0, s47
	s_nop 0
	global_load_lds_dwordx4 v[178:179], off
	v_lshl_add_u64 v[178:179], v[228:229], 0, s[12:13]
	s_mov_b32 m0, s48
	s_nop 0
	global_load_lds_dwordx4 v[178:179], off
	s_waitcnt vmcnt(8)
	s_waitcnt lgkmcnt(0)
	s_barrier
	s_waitcnt lgkmcnt(0)
	v_mfma_f32_16x16x32_bf16 v[60:63], v[128:131], v[192:195], v[60:63]
	v_mfma_f32_16x16x32_bf16 v[56:59], v[136:139], v[192:195], v[56:59]
	v_mfma_f32_16x16x32_bf16 v[44:47], v[128:131], v[200:203], v[44:47]
	v_mfma_f32_16x16x32_bf16 v[40:43], v[136:139], v[200:203], v[40:43]
	v_mfma_f32_16x16x32_bf16 v[28:31], v[128:131], v[208:211], v[28:31]
	v_mfma_f32_16x16x32_bf16 v[24:27], v[136:139], v[208:211], v[24:27]
	v_mfma_f32_16x16x32_bf16 v[12:15], v[128:131], v[216:219], v[12:15]
	v_mfma_f32_16x16x32_bf16 v[8:11], v[136:139], v[216:219], v[8:11]
	v_mfma_f32_16x16x32_bf16 v[60:63], v[132:135], v[196:199], v[60:63]
	v_mfma_f32_16x16x32_bf16 v[56:59], v[140:143], v[196:199], v[56:59]
	v_mfma_f32_16x16x32_bf16 v[44:47], v[132:135], v[204:207], v[44:47]
	v_mfma_f32_16x16x32_bf16 v[40:43], v[140:143], v[204:207], v[40:43]
	v_mfma_f32_16x16x32_bf16 v[28:31], v[132:135], v[212:215], v[28:31]
	v_mfma_f32_16x16x32_bf16 v[24:27], v[140:143], v[212:215], v[24:27]
	v_mfma_f32_16x16x32_bf16 v[12:15], v[132:135], v[220:223], v[12:15]
	v_mfma_f32_16x16x32_bf16 v[8:11], v[140:143], v[220:223], v[8:11]
	v_mfma_f32_16x16x32_bf16 v[52:55], v[166:169], v[192:195], v[52:55]
	v_mfma_f32_16x16x32_bf16 v[48:51], v[174:177], v[192:195], v[48:51]
	v_mfma_f32_16x16x32_bf16 v[36:39], v[166:169], v[200:203], v[36:39]
	v_mfma_f32_16x16x32_bf16 v[32:35], v[174:177], v[200:203], v[32:35]
	v_mfma_f32_16x16x32_bf16 v[20:23], v[166:169], v[208:211], v[20:23]
	v_mfma_f32_16x16x32_bf16 v[16:19], v[174:177], v[208:211], v[16:19]
	v_mfma_f32_16x16x32_bf16 v[4:7], v[166:169], v[216:219], v[4:7]
	v_mfma_f32_16x16x32_bf16 v[0:3], v[174:177], v[216:219], v[0:3]
	v_mfma_f32_16x16x32_bf16 v[52:55], v[170:173], v[196:199], v[52:55]
	v_mfma_f32_16x16x32_bf16 v[48:51], v[188:191], v[196:199], v[48:51]
	v_mfma_f32_16x16x32_bf16 v[36:39], v[170:173], v[204:207], v[36:39]
	v_mfma_f32_16x16x32_bf16 v[32:35], v[188:191], v[204:207], v[32:35]
	v_mfma_f32_16x16x32_bf16 v[20:23], v[170:173], v[212:215], v[20:23]
	v_mfma_f32_16x16x32_bf16 v[16:19], v[188:191], v[212:215], v[16:19]
	v_mfma_f32_16x16x32_bf16 v[4:7], v[170:173], v[220:223], v[4:7]
	v_mfma_f32_16x16x32_bf16 v[0:3], v[188:191], v[220:223], v[0:3]
	s_barrier
	s_add_i32 s56, s56, 2
	s_add_u32 s30, s30, 0x100
	s_addc_u32 s31, s31, 0
	s_add_u32 s54, s54, 0x100
	s_addc_u32 s55, s55, 0
	s_cmp_gt_u32 s56, 13
	s_cbranch_scc0 .LBB0_1781
	s_and_b64 vcc, exec, s[14:15]
	s_cbranch_vccz .LBB0_1784
	s_barrier

.LBB0_1870:
	ds_read_b128 v[148:151], v157
	ds_read_b128 v[152:155], v157 offset:1024
	ds_read_b128 v[164:167], v157 offset:2048
	ds_read_b128 v[168:171], v157 offset:3072
	ds_read_b128 v[172:175], v158
	ds_read_b128 v[176:179], v158 offset:1024
	ds_read_b128 v[184:187], v158 offset:2048
	ds_read_b128 v[188:191], v158 offset:3072
	s_add_u32 s34, s30, 0xfffc0080
	s_addc_u32 s35, s31, -1
	s_cmp_eq_u32 s55, 12
	s_cselect_b32 s37, s5, s35
	s_cselect_b32 s36, s11, s34
	s_cselect_b32 s35, s23, s54
	s_cselect_b32 s34, s25, s53
	v_lshl_add_u64 v[224:225], s[30:31], 0, v[138:139]
	s_add_i32 m0, s40, 0xc000
	ds_read_b128 v[192:195], v159
	ds_read_b128 v[196:199], v159 offset:1024
	ds_read_b128 v[200:203], v159 offset:2048
	ds_read_b128 v[204:207], v159 offset:3072
	ds_read_b128 v[208:211], v159 offset:4096
	ds_read_b128 v[212:215], v159 offset:5120
	ds_read_b128 v[216:219], v159 offset:6144
	ds_read_b128 v[220:223], v159 offset:7168
	global_load_lds_dwordx4 v[224:225], off
	v_lshl_add_u64 v[224:225], s[30:31], 0, v[140:141]
	s_add_i32 m0, s40, 0xe000
	s_nop 0
	global_load_lds_dwordx4 v[224:225], off
	s_waitcnt vmcnt(8)
	s_waitcnt lgkmcnt(0)
	s_barrier
	s_waitcnt lgkmcnt(0)
	v_mfma_f32_16x16x32_bf16 v[124:127], v[148:151], v[192:195], v[124:127]
	v_mfma_f32_16x16x32_bf16 v[120:123], v[164:167], v[192:195], v[120:123]
	v_mfma_f32_16x16x32_bf16 v[108:111], v[148:151], v[200:203], v[108:111]
	v_mfma_f32_16x16x32_bf16 v[104:107], v[164:167], v[200:203], v[104:107]
	v_mfma_f32_16x16x32_bf16 v[92:95], v[148:151], v[208:211], v[92:95]
	v_mfma_f32_16x16x32_bf16 v[88:91], v[164:167], v[208:211], v[88:91]
	v_mfma_f32_16x16x32_bf16 v[76:79], v[148:151], v[216:219], v[76:79]
	v_mfma_f32_16x16x32_bf16 v[72:75], v[164:167], v[216:219], v[72:75]
	v_mfma_f32_16x16x32_bf16 v[124:127], v[152:155], v[196:199], v[124:127]
	v_mfma_f32_16x16x32_bf16 v[120:123], v[168:171], v[196:199], v[120:123]
	v_mfma_f32_16x16x32_bf16 v[108:111], v[152:155], v[204:207], v[108:111]
	v_mfma_f32_16x16x32_bf16 v[104:107], v[168:171], v[204:207], v[104:107]
	v_mfma_f32_16x16x32_bf16 v[92:95], v[152:155], v[212:215], v[92:95]
	v_mfma_f32_16x16x32_bf16 v[88:91], v[168:171], v[212:215], v[88:91]
	v_mfma_f32_16x16x32_bf16 v[76:79], v[152:155], v[220:223], v[76:79]
	v_mfma_f32_16x16x32_bf16 v[72:75], v[168:171], v[220:223], v[72:75]
	v_mfma_f32_16x16x32_bf16 v[116:119], v[172:175], v[192:195], v[116:119]
	v_mfma_f32_16x16x32_bf16 v[112:115], v[184:187], v[192:195], v[112:115]
	v_mfma_f32_16x16x32_bf16 v[100:103], v[172:175], v[200:203], v[100:103]
	v_mfma_f32_16x16x32_bf16 v[96:99], v[184:187], v[200:203], v[96:99]
	v_mfma_f32_16x16x32_bf16 v[84:87], v[172:175], v[208:211], v[84:87]
	v_mfma_f32_16x16x32_bf16 v[80:83], v[184:187], v[208:211], v[80:83]
	v_mfma_f32_16x16x32_bf16 v[68:71], v[172:175], v[216:219], v[68:71]
	v_mfma_f32_16x16x32_bf16 v[64:67], v[184:187], v[216:219], v[64:67]
	v_mfma_f32_16x16x32_bf16 v[116:119], v[176:179], v[196:199], v[116:119]
	v_mfma_f32_16x16x32_bf16 v[112:115], v[188:191], v[196:199], v[112:115]
	v_mfma_f32_16x16x32_bf16 v[100:103], v[176:179], v[204:207], v[100:103]
	v_mfma_f32_16x16x32_bf16 v[96:99], v[188:191], v[204:207], v[96:99]
	v_mfma_f32_16x16x32_bf16 v[84:87], v[176:179], v[212:215], v[84:87]
	v_mfma_f32_16x16x32_bf16 v[80:83], v[188:191], v[212:215], v[80:83]
	v_mfma_f32_16x16x32_bf16 v[68:71], v[176:179], v[220:223], v[68:71]
	v_mfma_f32_16x16x32_bf16 v[64:67], v[188:191], v[220:223], v[64:67]
	s_barrier
	s_add_i32 s56, s50, s39
	v_lshl_add_u64 v[224:225], s[34:35], 0, v[130:131]
	s_mov_b32 m0, s56
	ds_read_b128 v[192:195], v159 offset:16384
	ds_read_b128 v[196:199], v159 offset:17408
	ds_read_b128 v[200:203], v159 offset:18432
	ds_read_b128 v[204:207], v159 offset:19456
	ds_read_b128 v[208:211], v159 offset:20480
	ds_read_b128 v[212:215], v159 offset:21504
	ds_read_b128 v[216:219], v159 offset:22528
	ds_read_b128 v[220:223], v159 offset:23552
	global_load_lds_dwordx4 v[224:225], off
	s_add_i32 m0, s56, 0x2000
	s_add_u32 s56, s34, 0x40000
	v_lshl_add_u64 v[226:227], s[34:35], 0, v[134:135]
	s_addc_u32 s57, s35, 0
	s_add_i32 s58, s51, s39
	global_load_lds_dwordx4 v[226:227], off
	v_lshl_add_u64 v[228:229], s[56:57], 0, v[130:131]
	s_mov_b32 m0, s58
	v_lshl_add_u64 v[230:231], s[36:37], 0, v[132:133]
	global_load_lds_dwordx4 v[228:229], off
	v_lshl_add_u64 v[228:229], s[56:57], 0, v[134:135]
	s_add_i32 m0, s58, 0x2000
	s_nop 0
	global_load_lds_dwordx4 v[228:229], off
	v_lshl_add_u64 v[228:229], s[36:37], 0, v[128:129]
	s_mov_b32 m0, s40
	s_nop 0
	global_load_lds_dwordx4 v[228:229], off
	s_mov_b32 m0, s41
	s_nop 0
	global_load_lds_dwordx4 v[230:231], off
	s_waitcnt vmcnt(8)
	s_waitcnt lgkmcnt(0)
	s_barrier
	s_waitcnt lgkmcnt(0)
	v_mfma_f32_16x16x32_bf16 v[60:63], v[148:151], v[192:195], v[60:63]
	v_mfma_f32_16x16x32_bf16 v[56:59], v[164:167], v[192:195], v[56:59]
	v_mfma_f32_16x16x32_bf16 v[44:47], v[148:151], v[200:203], v[44:47]
	v_mfma_f32_16x16x32_bf16 v[40:43], v[164:167], v[200:203], v[40:43]
	v_mfma_f32_16x16x32_bf16 v[28:31], v[148:151], v[208:211], v[28:31]
	v_mfma_f32_16x16x32_bf16 v[24:27], v[164:167], v[208:211], v[24:27]
	v_mfma_f32_16x16x32_bf16 v[12:15], v[148:151], v[216:219], v[12:15]
	v_mfma_f32_16x16x32_bf16 v[8:11], v[164:167], v[216:219], v[8:11]
	v_mfma_f32_16x16x32_bf16 v[60:63], v[152:155], v[196:199], v[60:63]
	v_mfma_f32_16x16x32_bf16 v[56:59], v[168:171], v[196:199], v[56:59]
	v_mfma_f32_16x16x32_bf16 v[44:47], v[152:155], v[204:207], v[44:47]
	v_mfma_f32_16x16x32_bf16 v[40:43], v[168:171], v[204:207], v[40:43]
	v_mfma_f32_16x16x32_bf16 v[28:31], v[152:155], v[212:215], v[28:31]
	v_mfma_f32_16x16x32_bf16 v[24:27], v[168:171], v[212:215], v[24:27]
	v_mfma_f32_16x16x32_bf16 v[12:15], v[152:155], v[220:223], v[12:15]
	v_mfma_f32_16x16x32_bf16 v[8:11], v[168:171], v[220:223], v[8:11]
	v_mfma_f32_16x16x32_bf16 v[52:55], v[172:175], v[192:195], v[52:55]
	v_mfma_f32_16x16x32_bf16 v[48:51], v[184:187], v[192:195], v[48:51]
	v_mfma_f32_16x16x32_bf16 v[36:39], v[172:175], v[200:203], v[36:39]
	v_mfma_f32_16x16x32_bf16 v[32:35], v[184:187], v[200:203], v[32:35]
	v_mfma_f32_16x16x32_bf16 v[20:23], v[172:175], v[208:211], v[20:23]
	v_mfma_f32_16x16x32_bf16 v[16:19], v[184:187], v[208:211], v[16:19]
	v_mfma_f32_16x16x32_bf16 v[4:7], v[172:175], v[216:219], v[4:7]
	v_mfma_f32_16x16x32_bf16 v[0:3], v[184:187], v[216:219], v[0:3]
	v_mfma_f32_16x16x32_bf16 v[52:55], v[176:179], v[196:199], v[52:55]
	v_mfma_f32_16x16x32_bf16 v[48:51], v[188:191], v[196:199], v[48:51]
	v_mfma_f32_16x16x32_bf16 v[36:39], v[176:179], v[204:207], v[36:39]
	v_mfma_f32_16x16x32_bf16 v[32:35], v[188:191], v[204:207], v[32:35]
	v_mfma_f32_16x16x32_bf16 v[20:23], v[176:179], v[212:215], v[20:23]
	v_mfma_f32_16x16x32_bf16 v[16:19], v[188:191], v[212:215], v[16:19]
	v_mfma_f32_16x16x32_bf16 v[4:7], v[176:179], v[220:223], v[4:7]
	v_mfma_f32_16x16x32_bf16 v[0:3], v[188:191], v[220:223], v[0:3]
	s_barrier
	s_add_i32 s56, 0, 0x18000
	v_add_u32_e32 v163, s56, v156
	s_add_i32 s57, 0, 0x1c000
	ds_read_b128 v[148:151], v163
	ds_read_b128 v[152:155], v163 offset:1024
	ds_read_b128 v[164:167], v163 offset:2048
	ds_read_b128 v[168:171], v163 offset:3072
	v_add_u32_e32 v163, s57, v156
	ds_read_b128 v[172:175], v163
	ds_read_b128 v[176:179], v163 offset:1024
	ds_read_b128 v[184:187], v163 offset:2048
	ds_read_b128 v[188:191], v163 offset:3072
	s_add_u32 s36, s36, 0x40000
	s_addc_u32 s37, s37, 0
	s_mov_b32 m0, s42
	v_lshl_add_u64 v[232:233], s[36:37], 0, v[128:129]
	ds_read_b128 v[192:195], v159 offset:32768
	ds_read_b128 v[196:199], v159 offset:33792
	ds_read_b128 v[200:203], v159 offset:34816
	ds_read_b128 v[204:207], v159 offset:35840
	ds_read_b128 v[208:211], v159 offset:36864
	ds_read_b128 v[212:215], v159 offset:37888
	ds_read_b128 v[216:219], v159 offset:38912
	ds_read_b128 v[220:223], v159 offset:39936
	global_load_lds_dwordx4 v[232:233], off
	v_lshl_add_u64 v[232:233], s[36:37], 0, v[132:133]
	s_mov_b32 m0, s43
	s_nop 0
	global_load_lds_dwordx4 v[232:233], off
	s_waitcnt vmcnt(8)
	s_waitcnt lgkmcnt(0)
	s_barrier
	s_waitcnt lgkmcnt(0)
	v_mfma_f32_16x16x32_bf16 v[124:127], v[148:151], v[192:195], v[124:127]
	v_mfma_f32_16x16x32_bf16 v[120:123], v[164:167], v[192:195], v[120:123]
	v_mfma_f32_16x16x32_bf16 v[108:111], v[148:151], v[200:203], v[108:111]
	v_mfma_f32_16x16x32_bf16 v[104:107], v[164:167], v[200:203], v[104:107]
	v_mfma_f32_16x16x32_bf16 v[92:95], v[148:151], v[208:211], v[92:95]
	v_mfma_f32_16x16x32_bf16 v[88:91], v[164:167], v[208:211], v[88:91]
	v_mfma_f32_16x16x32_bf16 v[76:79], v[148:151], v[216:219], v[76:79]
	v_mfma_f32_16x16x32_bf16 v[72:75], v[164:167], v[216:219], v[72:75]
	v_mfma_f32_16x16x32_bf16 v[124:127], v[152:155], v[196:199], v[124:127]
	v_mfma_f32_16x16x32_bf16 v[120:123], v[168:171], v[196:199], v[120:123]
	v_mfma_f32_16x16x32_bf16 v[108:111], v[152:155], v[204:207], v[108:111]
	v_mfma_f32_16x16x32_bf16 v[104:107], v[168:171], v[204:207], v[104:107]
	v_mfma_f32_16x16x32_bf16 v[92:95], v[152:155], v[212:215], v[92:95]
	v_mfma_f32_16x16x32_bf16 v[88:91], v[168:171], v[212:215], v[88:91]
	v_mfma_f32_16x16x32_bf16 v[76:79], v[152:155], v[220:223], v[76:79]
	v_mfma_f32_16x16x32_bf16 v[72:75], v[168:171], v[220:223], v[72:75]
	v_mfma_f32_16x16x32_bf16 v[116:119], v[172:175], v[192:195], v[116:119]
	v_mfma_f32_16x16x32_bf16 v[112:115], v[184:187], v[192:195], v[112:115]
	v_mfma_f32_16x16x32_bf16 v[100:103], v[172:175], v[200:203], v[100:103]
	v_mfma_f32_16x16x32_bf16 v[96:99], v[184:187], v[200:203], v[96:99]
	v_mfma_f32_16x16x32_bf16 v[84:87], v[172:175], v[208:211], v[84:87]
	v_mfma_f32_16x16x32_bf16 v[80:83], v[184:187], v[208:211], v[80:83]
	v_mfma_f32_16x16x32_bf16 v[68:71], v[172:175], v[216:219], v[68:71]
	v_mfma_f32_16x16x32_bf16 v[64:67], v[184:187], v[216:219], v[64:67]
	v_mfma_f32_16x16x32_bf16 v[116:119], v[176:179], v[196:199], v[116:119]
	v_mfma_f32_16x16x32_bf16 v[112:115], v[188:191], v[196:199], v[112:115]
	v_mfma_f32_16x16x32_bf16 v[100:103], v[176:179], v[204:207], v[100:103]
	v_mfma_f32_16x16x32_bf16 v[96:99], v[188:191], v[204:207], v[96:99]
	v_mfma_f32_16x16x32_bf16 v[84:87], v[176:179], v[212:215], v[84:87]
	v_mfma_f32_16x16x32_bf16 v[80:83], v[188:191], v[212:215], v[80:83]
	v_mfma_f32_16x16x32_bf16 v[68:71], v[176:179], v[220:223], v[68:71]
	v_mfma_f32_16x16x32_bf16 v[64:67], v[188:191], v[220:223], v[64:67]
	s_barrier
	s_add_i32 s36, s56, s39
	v_lshl_add_u64 v[224:225], v[224:225], 0, s[18:19]
	s_mov_b32 m0, s36
	ds_read_b128 v[192:195], v159 offset:49152
	ds_read_b128 v[196:199], v159 offset:50176
	ds_read_b128 v[200:203], v159 offset:51200
	ds_read_b128 v[204:207], v159 offset:52224
	ds_read_b128 v[208:211], v159 offset:53248
	ds_read_b128 v[212:215], v159 offset:54272
	ds_read_b128 v[216:219], v159 offset:55296
	ds_read_b128 v[220:223], v159 offset:56320
	global_load_lds_dwordx4 v[224:225], off
	s_add_i32 m0, s36, 0x2000
	s_add_u32 s34, s34, 0x40080
	v_lshl_add_u64 v[224:225], v[226:227], 0, s[18:19]
	s_addc_u32 s35, s35, 0
	s_add_i32 s36, s57, s39
	global_load_lds_dwordx4 v[224:225], off
	v_lshl_add_u64 v[224:225], s[34:35], 0, v[130:131]
	s_mov_b32 m0, s36
	s_nop 0
	global_load_lds_dwordx4 v[224:225], off
	v_lshl_add_u64 v[224:225], s[34:35], 0, v[134:135]
	s_add_i32 m0, s36, 0x2000
	s_nop 0
	global_load_lds_dwordx4 v[224:225], off
	v_lshl_add_u64 v[224:225], v[228:229], 0, s[18:19]
	s_mov_b32 m0, s45
	s_nop 0
	global_load_lds_dwordx4 v[224:225], off
	v_lshl_add_u64 v[224:225], v[230:231], 0, s[18:19]
	s_mov_b32 m0, s46
	s_nop 0
	global_load_lds_dwordx4 v[224:225], off
	s_waitcnt vmcnt(8)
	s_waitcnt lgkmcnt(0)
	s_barrier
	s_waitcnt lgkmcnt(0)
	v_mfma_f32_16x16x32_bf16 v[60:63], v[148:151], v[192:195], v[60:63]
	v_mfma_f32_16x16x32_bf16 v[56:59], v[164:167], v[192:195], v[56:59]
	v_mfma_f32_16x16x32_bf16 v[44:47], v[148:151], v[200:203], v[44:47]
	v_mfma_f32_16x16x32_bf16 v[40:43], v[164:167], v[200:203], v[40:43]
	v_mfma_f32_16x16x32_bf16 v[28:31], v[148:151], v[208:211], v[28:31]
	v_mfma_f32_16x16x32_bf16 v[24:27], v[164:167], v[208:211], v[24:27]
	v_mfma_f32_16x16x32_bf16 v[12:15], v[148:151], v[216:219], v[12:15]
	v_mfma_f32_16x16x32_bf16 v[8:11], v[164:167], v[216:219], v[8:11]
	v_mfma_f32_16x16x32_bf16 v[60:63], v[152:155], v[196:199], v[60:63]
	v_mfma_f32_16x16x32_bf16 v[56:59], v[168:171], v[196:199], v[56:59]
	v_mfma_f32_16x16x32_bf16 v[44:47], v[152:155], v[204:207], v[44:47]
	v_mfma_f32_16x16x32_bf16 v[40:43], v[168:171], v[204:207], v[40:43]
	v_mfma_f32_16x16x32_bf16 v[28:31], v[152:155], v[212:215], v[28:31]
	v_mfma_f32_16x16x32_bf16 v[24:27], v[168:171], v[212:215], v[24:27]
	v_mfma_f32_16x16x32_bf16 v[12:15], v[152:155], v[220:223], v[12:15]
	v_mfma_f32_16x16x32_bf16 v[8:11], v[168:171], v[220:223], v[8:11]
	v_mfma_f32_16x16x32_bf16 v[52:55], v[172:175], v[192:195], v[52:55]
	v_mfma_f32_16x16x32_bf16 v[48:51], v[184:187], v[192:195], v[48:51]
	v_mfma_f32_16x16x32_bf16 v[36:39], v[172:175], v[200:203], v[36:39]
	v_mfma_f32_16x16x32_bf16 v[32:35], v[184:187], v[200:203], v[32:35]
	v_mfma_f32_16x16x32_bf16 v[20:23], v[172:175], v[208:211], v[20:23]
	v_mfma_f32_16x16x32_bf16 v[16:19], v[184:187], v[208:211], v[16:19]
	v_mfma_f32_16x16x32_bf16 v[4:7], v[172:175], v[216:219], v[4:7]
	v_mfma_f32_16x16x32_bf16 v[0:3], v[184:187], v[216:219], v[0:3]
	v_mfma_f32_16x16x32_bf16 v[52:55], v[176:179], v[196:199], v[52:55]
	v_mfma_f32_16x16x32_bf16 v[48:51], v[188:191], v[196:199], v[48:51]
	v_mfma_f32_16x16x32_bf16 v[36:39], v[176:179], v[204:207], v[36:39]
	v_mfma_f32_16x16x32_bf16 v[32:35], v[188:191], v[204:207], v[32:35]
	v_mfma_f32_16x16x32_bf16 v[20:23], v[176:179], v[212:215], v[20:23]
	v_mfma_f32_16x16x32_bf16 v[16:19], v[188:191], v[212:215], v[16:19]
	v_mfma_f32_16x16x32_bf16 v[4:7], v[176:179], v[220:223], v[4:7]
	v_mfma_f32_16x16x32_bf16 v[0:3], v[188:191], v[220:223], v[0:3]
	s_barrier
	s_add_i32 s55, s55, 2
	s_add_u32 s30, s30, 0x100
	s_addc_u32 s31, s31, 0
	s_add_u32 s53, s53, 0x100
	s_addc_u32 s54, s54, 0
	s_cmp_gt_u32 s55, 13
	s_cbranch_scc0 .LBB0_1870
	s_and_b64 vcc, exec, s[20:21]
	s_cbranch_vccz .LBB0_1873
	s_barrier

.LBB0_2022:
	ds_read_b128 v[128:131], v178
	ds_read_b128 v[132:135], v178 offset:1024
	ds_read_b128 v[136:139], v178 offset:2048
	ds_read_b128 v[140:143], v178 offset:3072
	ds_read_b128 v[164:167], v179
	ds_read_b128 v[168:171], v179 offset:1024
	ds_read_b128 v[172:175], v179 offset:2048
	ds_read_b128 v[184:187], v179 offset:3072
	s_add_u32 s34, s30, 0xfffc0080
	s_addc_u32 s35, s31, -1
	s_cmp_eq_u32 s56, 12
	s_cselect_b32 s37, s21, s35
	s_cselect_b32 s36, s27, s34
	s_cselect_b32 s35, s19, s55
	s_cselect_b32 s34, s29, s54
	v_lshl_add_u64 v[220:221], s[30:31], 0, v[156:157]
	s_add_i32 m0, s42, 0xc000
	ds_read_b128 v[188:191], v180
	ds_read_b128 v[192:195], v180 offset:1024
	ds_read_b128 v[196:199], v180 offset:2048
	ds_read_b128 v[200:203], v180 offset:3072
	ds_read_b128 v[204:207], v180 offset:4096
	ds_read_b128 v[208:211], v180 offset:5120
	ds_read_b128 v[212:215], v180 offset:6144
	ds_read_b128 v[216:219], v180 offset:7168
	global_load_lds_dwordx4 v[220:221], off
	v_lshl_add_u64 v[220:221], s[30:31], 0, v[158:159]
	s_add_i32 m0, s42, 0xe000
	s_nop 0
	global_load_lds_dwordx4 v[220:221], off
	s_waitcnt vmcnt(8)
	s_waitcnt lgkmcnt(0)
	s_barrier
	s_waitcnt lgkmcnt(0)
	v_mfma_f32_16x16x32_bf16 v[124:127], v[128:131], v[188:191], v[124:127]
	v_mfma_f32_16x16x32_bf16 v[120:123], v[136:139], v[188:191], v[120:123]
	v_mfma_f32_16x16x32_bf16 v[108:111], v[128:131], v[196:199], v[108:111]
	v_mfma_f32_16x16x32_bf16 v[104:107], v[136:139], v[196:199], v[104:107]
	v_mfma_f32_16x16x32_bf16 v[92:95], v[128:131], v[204:207], v[92:95]
	v_mfma_f32_16x16x32_bf16 v[88:91], v[136:139], v[204:207], v[88:91]
	v_mfma_f32_16x16x32_bf16 v[76:79], v[128:131], v[212:215], v[76:79]
	v_mfma_f32_16x16x32_bf16 v[72:75], v[136:139], v[212:215], v[72:75]
	v_mfma_f32_16x16x32_bf16 v[124:127], v[132:135], v[192:195], v[124:127]
	v_mfma_f32_16x16x32_bf16 v[120:123], v[140:143], v[192:195], v[120:123]
	v_mfma_f32_16x16x32_bf16 v[108:111], v[132:135], v[200:203], v[108:111]
	v_mfma_f32_16x16x32_bf16 v[104:107], v[140:143], v[200:203], v[104:107]
	v_mfma_f32_16x16x32_bf16 v[92:95], v[132:135], v[208:211], v[92:95]
	v_mfma_f32_16x16x32_bf16 v[88:91], v[140:143], v[208:211], v[88:91]
	v_mfma_f32_16x16x32_bf16 v[76:79], v[132:135], v[216:219], v[76:79]
	v_mfma_f32_16x16x32_bf16 v[72:75], v[140:143], v[216:219], v[72:75]
	v_mfma_f32_16x16x32_bf16 v[116:119], v[164:167], v[188:191], v[116:119]
	v_mfma_f32_16x16x32_bf16 v[112:115], v[172:175], v[188:191], v[112:115]
	v_mfma_f32_16x16x32_bf16 v[100:103], v[164:167], v[196:199], v[100:103]
	v_mfma_f32_16x16x32_bf16 v[96:99], v[172:175], v[196:199], v[96:99]
	v_mfma_f32_16x16x32_bf16 v[84:87], v[164:167], v[204:207], v[84:87]
	v_mfma_f32_16x16x32_bf16 v[80:83], v[172:175], v[204:207], v[80:83]
	v_mfma_f32_16x16x32_bf16 v[68:71], v[164:167], v[212:215], v[68:71]
	v_mfma_f32_16x16x32_bf16 v[64:67], v[172:175], v[212:215], v[64:67]
	v_mfma_f32_16x16x32_bf16 v[116:119], v[168:171], v[192:195], v[116:119]
	v_mfma_f32_16x16x32_bf16 v[112:115], v[184:187], v[192:195], v[112:115]
	v_mfma_f32_16x16x32_bf16 v[100:103], v[168:171], v[200:203], v[100:103]
	v_mfma_f32_16x16x32_bf16 v[96:99], v[184:187], v[200:203], v[96:99]
	v_mfma_f32_16x16x32_bf16 v[84:87], v[168:171], v[208:211], v[84:87]
	v_mfma_f32_16x16x32_bf16 v[80:83], v[184:187], v[208:211], v[80:83]
	v_mfma_f32_16x16x32_bf16 v[68:71], v[168:171], v[216:219], v[68:71]
	v_mfma_f32_16x16x32_bf16 v[64:67], v[184:187], v[216:219], v[64:67]
	s_barrier
	s_add_i32 s57, s52, s41
	v_lshl_add_u64 v[220:221], s[34:35], 0, v[146:147]
	s_mov_b32 m0, s57
	ds_read_b128 v[188:191], v180 offset:16384
	ds_read_b128 v[192:195], v180 offset:17408
	ds_read_b128 v[196:199], v180 offset:18432
	ds_read_b128 v[200:203], v180 offset:19456
	ds_read_b128 v[204:207], v180 offset:20480
	ds_read_b128 v[208:211], v180 offset:21504
	ds_read_b128 v[212:215], v180 offset:22528
	ds_read_b128 v[216:219], v180 offset:23552
	global_load_lds_dwordx4 v[220:221], off
	s_add_i32 m0, s57, 0x2000
	s_add_u32 s58, s34, 0x40000
	v_lshl_add_u64 v[222:223], s[34:35], 0, v[150:151]
	s_addc_u32 s59, s35, 0
	s_add_i32 s57, s53, s41
	global_load_lds_dwordx4 v[222:223], off
	v_lshl_add_u64 v[224:225], s[58:59], 0, v[146:147]
	s_mov_b32 m0, s57
	v_lshl_add_u64 v[226:227], s[36:37], 0, v[148:149]
	global_load_lds_dwordx4 v[224:225], off
	v_lshl_add_u64 v[224:225], s[58:59], 0, v[150:151]
	s_add_i32 m0, s57, 0x2000
	s_nop 0
	global_load_lds_dwordx4 v[224:225], off
	v_lshl_add_u64 v[224:225], s[36:37], 0, v[144:145]
	s_mov_b32 m0, s42
	s_nop 0
	global_load_lds_dwordx4 v[224:225], off
	s_mov_b32 m0, s43
	s_nop 0
	global_load_lds_dwordx4 v[226:227], off
	s_waitcnt vmcnt(8)
	s_waitcnt lgkmcnt(0)
	s_barrier
	s_waitcnt lgkmcnt(0)
	v_mfma_f32_16x16x32_bf16 v[60:63], v[128:131], v[188:191], v[60:63]
	v_mfma_f32_16x16x32_bf16 v[56:59], v[136:139], v[188:191], v[56:59]
	v_mfma_f32_16x16x32_bf16 v[44:47], v[128:131], v[196:199], v[44:47]
	v_mfma_f32_16x16x32_bf16 v[40:43], v[136:139], v[196:199], v[40:43]
	v_mfma_f32_16x16x32_bf16 v[28:31], v[128:131], v[204:207], v[28:31]
	v_mfma_f32_16x16x32_bf16 v[24:27], v[136:139], v[204:207], v[24:27]
	v_mfma_f32_16x16x32_bf16 v[12:15], v[128:131], v[212:215], v[12:15]
	v_mfma_f32_16x16x32_bf16 v[8:11], v[136:139], v[212:215], v[8:11]
	v_mfma_f32_16x16x32_bf16 v[60:63], v[132:135], v[192:195], v[60:63]
	v_mfma_f32_16x16x32_bf16 v[56:59], v[140:143], v[192:195], v[56:59]
	v_mfma_f32_16x16x32_bf16 v[44:47], v[132:135], v[200:203], v[44:47]
	v_mfma_f32_16x16x32_bf16 v[40:43], v[140:143], v[200:203], v[40:43]
	v_mfma_f32_16x16x32_bf16 v[28:31], v[132:135], v[208:211], v[28:31]
	v_mfma_f32_16x16x32_bf16 v[24:27], v[140:143], v[208:211], v[24:27]
	v_mfma_f32_16x16x32_bf16 v[12:15], v[132:135], v[216:219], v[12:15]
	v_mfma_f32_16x16x32_bf16 v[8:11], v[140:143], v[216:219], v[8:11]
	v_mfma_f32_16x16x32_bf16 v[52:55], v[164:167], v[188:191], v[52:55]
	v_mfma_f32_16x16x32_bf16 v[48:51], v[172:175], v[188:191], v[48:51]
	v_mfma_f32_16x16x32_bf16 v[36:39], v[164:167], v[196:199], v[36:39]
	v_mfma_f32_16x16x32_bf16 v[32:35], v[172:175], v[196:199], v[32:35]
	v_mfma_f32_16x16x32_bf16 v[20:23], v[164:167], v[204:207], v[20:23]
	v_mfma_f32_16x16x32_bf16 v[16:19], v[172:175], v[204:207], v[16:19]
	v_mfma_f32_16x16x32_bf16 v[4:7], v[164:167], v[212:215], v[4:7]
	v_mfma_f32_16x16x32_bf16 v[0:3], v[172:175], v[212:215], v[0:3]
	v_mfma_f32_16x16x32_bf16 v[52:55], v[168:171], v[192:195], v[52:55]
	v_mfma_f32_16x16x32_bf16 v[48:51], v[184:187], v[192:195], v[48:51]
	v_mfma_f32_16x16x32_bf16 v[36:39], v[168:171], v[200:203], v[36:39]
	v_mfma_f32_16x16x32_bf16 v[32:35], v[184:187], v[200:203], v[32:35]
	v_mfma_f32_16x16x32_bf16 v[20:23], v[168:171], v[208:211], v[20:23]
	v_mfma_f32_16x16x32_bf16 v[16:19], v[184:187], v[208:211], v[16:19]
	v_mfma_f32_16x16x32_bf16 v[4:7], v[168:171], v[216:219], v[4:7]
	v_mfma_f32_16x16x32_bf16 v[0:3], v[184:187], v[216:219], v[0:3]
	s_barrier
	s_add_i32 s57, 0, 0x18000
	s_add_i32 s58, 0, 0x1c000
	v_add_u32_e32 v140, s57, v177
	v_add_u32_e32 v183, s58, v177
	ds_read_b128 v[128:131], v140
	ds_read_b128 v[132:135], v140 offset:1024
	ds_read_b128 v[136:139], v140 offset:2048
	ds_read_b128 v[140:143], v140 offset:3072
	ds_read_b128 v[164:167], v183
	ds_read_b128 v[168:171], v183 offset:1024
	ds_read_b128 v[172:175], v183 offset:2048
	ds_read_b128 v[184:187], v183 offset:3072
	s_add_u32 s36, s36, 0x40000
	s_addc_u32 s37, s37, 0
	s_mov_b32 m0, s44
	v_lshl_add_u64 v[228:229], s[36:37], 0, v[144:145]
	ds_read_b128 v[188:191], v180 offset:32768
	ds_read_b128 v[192:195], v180 offset:33792
	ds_read_b128 v[196:199], v180 offset:34816
	ds_read_b128 v[200:203], v180 offset:35840
	ds_read_b128 v[204:207], v180 offset:36864
	ds_read_b128 v[208:211], v180 offset:37888
	ds_read_b128 v[212:215], v180 offset:38912
	ds_read_b128 v[216:219], v180 offset:39936
	global_load_lds_dwordx4 v[228:229], off
	v_lshl_add_u64 v[228:229], s[36:37], 0, v[148:149]
	s_mov_b32 m0, s45
	s_nop 0
	global_load_lds_dwordx4 v[228:229], off
	s_waitcnt vmcnt(8)
	s_waitcnt lgkmcnt(0)
	s_barrier
	s_waitcnt lgkmcnt(0)
	v_mfma_f32_16x16x32_bf16 v[124:127], v[128:131], v[188:191], v[124:127]
	v_mfma_f32_16x16x32_bf16 v[120:123], v[136:139], v[188:191], v[120:123]
	v_mfma_f32_16x16x32_bf16 v[108:111], v[128:131], v[196:199], v[108:111]
	v_mfma_f32_16x16x32_bf16 v[104:107], v[136:139], v[196:199], v[104:107]
	v_mfma_f32_16x16x32_bf16 v[92:95], v[128:131], v[204:207], v[92:95]
	v_mfma_f32_16x16x32_bf16 v[88:91], v[136:139], v[204:207], v[88:91]
	v_mfma_f32_16x16x32_bf16 v[76:79], v[128:131], v[212:215], v[76:79]
	v_mfma_f32_16x16x32_bf16 v[72:75], v[136:139], v[212:215], v[72:75]
	v_mfma_f32_16x16x32_bf16 v[124:127], v[132:135], v[192:195], v[124:127]
	v_mfma_f32_16x16x32_bf16 v[120:123], v[140:143], v[192:195], v[120:123]
	v_mfma_f32_16x16x32_bf16 v[108:111], v[132:135], v[200:203], v[108:111]
	v_mfma_f32_16x16x32_bf16 v[104:107], v[140:143], v[200:203], v[104:107]
	v_mfma_f32_16x16x32_bf16 v[92:95], v[132:135], v[208:211], v[92:95]
	v_mfma_f32_16x16x32_bf16 v[88:91], v[140:143], v[208:211], v[88:91]
	v_mfma_f32_16x16x32_bf16 v[76:79], v[132:135], v[216:219], v[76:79]
	v_mfma_f32_16x16x32_bf16 v[72:75], v[140:143], v[216:219], v[72:75]
	v_mfma_f32_16x16x32_bf16 v[116:119], v[164:167], v[188:191], v[116:119]
	v_mfma_f32_16x16x32_bf16 v[112:115], v[172:175], v[188:191], v[112:115]
	v_mfma_f32_16x16x32_bf16 v[100:103], v[164:167], v[196:199], v[100:103]
	v_mfma_f32_16x16x32_bf16 v[96:99], v[172:175], v[196:199], v[96:99]
	v_mfma_f32_16x16x32_bf16 v[84:87], v[164:167], v[204:207], v[84:87]
	v_mfma_f32_16x16x32_bf16 v[80:83], v[172:175], v[204:207], v[80:83]
	v_mfma_f32_16x16x32_bf16 v[68:71], v[164:167], v[212:215], v[68:71]
	v_mfma_f32_16x16x32_bf16 v[64:67], v[172:175], v[212:215], v[64:67]
	v_mfma_f32_16x16x32_bf16 v[116:119], v[168:171], v[192:195], v[116:119]
	v_mfma_f32_16x16x32_bf16 v[112:115], v[184:187], v[192:195], v[112:115]
	v_mfma_f32_16x16x32_bf16 v[100:103], v[168:171], v[200:203], v[100:103]
	v_mfma_f32_16x16x32_bf16 v[96:99], v[184:187], v[200:203], v[96:99]
	v_mfma_f32_16x16x32_bf16 v[84:87], v[168:171], v[208:211], v[84:87]
	v_mfma_f32_16x16x32_bf16 v[80:83], v[184:187], v[208:211], v[80:83]
	v_mfma_f32_16x16x32_bf16 v[68:71], v[168:171], v[216:219], v[68:71]
	v_mfma_f32_16x16x32_bf16 v[64:67], v[184:187], v[216:219], v[64:67]
	s_barrier
	s_add_i32 s36, s57, s41
	v_lshl_add_u64 v[220:221], v[220:221], 0, s[12:13]
	s_mov_b32 m0, s36
	ds_read_b128 v[188:191], v180 offset:49152
	ds_read_b128 v[192:195], v180 offset:50176
	ds_read_b128 v[196:199], v180 offset:51200
	ds_read_b128 v[200:203], v180 offset:52224
	ds_read_b128 v[204:207], v180 offset:53248
	ds_read_b128 v[208:211], v180 offset:54272
	ds_read_b128 v[212:215], v180 offset:55296
	ds_read_b128 v[216:219], v180 offset:56320
	global_load_lds_dwordx4 v[220:221], off
	s_add_i32 m0, s36, 0x2000
	s_add_u32 s34, s34, 0x40080
	v_lshl_add_u64 v[220:221], v[222:223], 0, s[12:13]
	s_addc_u32 s35, s35, 0
	s_add_i32 s36, s58, s41
	global_load_lds_dwordx4 v[220:221], off
	v_lshl_add_u64 v[220:221], s[34:35], 0, v[146:147]
	s_mov_b32 m0, s36
	s_nop 0
	global_load_lds_dwordx4 v[220:221], off
	v_lshl_add_u64 v[220:221], s[34:35], 0, v[150:151]
	s_add_i32 m0, s36, 0x2000
	s_nop 0
	global_load_lds_dwordx4 v[220:221], off
	v_lshl_add_u64 v[220:221], v[224:225], 0, s[12:13]
	s_mov_b32 m0, s47
	s_nop 0
	global_load_lds_dwordx4 v[220:221], off
	v_lshl_add_u64 v[220:221], v[226:227], 0, s[12:13]
	s_mov_b32 m0, s48
	s_nop 0
	global_load_lds_dwordx4 v[220:221], off
	s_waitcnt vmcnt(8)
	s_waitcnt lgkmcnt(0)
	s_barrier
	s_waitcnt lgkmcnt(0)
	v_mfma_f32_16x16x32_bf16 v[60:63], v[128:131], v[188:191], v[60:63]
	v_mfma_f32_16x16x32_bf16 v[56:59], v[136:139], v[188:191], v[56:59]
	v_mfma_f32_16x16x32_bf16 v[44:47], v[128:131], v[196:199], v[44:47]
	v_mfma_f32_16x16x32_bf16 v[40:43], v[136:139], v[196:199], v[40:43]
	v_mfma_f32_16x16x32_bf16 v[28:31], v[128:131], v[204:207], v[28:31]
	v_mfma_f32_16x16x32_bf16 v[24:27], v[136:139], v[204:207], v[24:27]
	v_mfma_f32_16x16x32_bf16 v[12:15], v[128:131], v[212:215], v[12:15]
	v_mfma_f32_16x16x32_bf16 v[8:11], v[136:139], v[212:215], v[8:11]
	v_mfma_f32_16x16x32_bf16 v[60:63], v[132:135], v[192:195], v[60:63]
	v_mfma_f32_16x16x32_bf16 v[56:59], v[140:143], v[192:195], v[56:59]
	v_mfma_f32_16x16x32_bf16 v[44:47], v[132:135], v[200:203], v[44:47]
	v_mfma_f32_16x16x32_bf16 v[40:43], v[140:143], v[200:203], v[40:43]
	v_mfma_f32_16x16x32_bf16 v[28:31], v[132:135], v[208:211], v[28:31]
	v_mfma_f32_16x16x32_bf16 v[24:27], v[140:143], v[208:211], v[24:27]
	v_mfma_f32_16x16x32_bf16 v[12:15], v[132:135], v[216:219], v[12:15]
	v_mfma_f32_16x16x32_bf16 v[8:11], v[140:143], v[216:219], v[8:11]
	v_mfma_f32_16x16x32_bf16 v[52:55], v[164:167], v[188:191], v[52:55]
	v_mfma_f32_16x16x32_bf16 v[48:51], v[172:175], v[188:191], v[48:51]
	v_mfma_f32_16x16x32_bf16 v[36:39], v[164:167], v[196:199], v[36:39]
	v_mfma_f32_16x16x32_bf16 v[32:35], v[172:175], v[196:199], v[32:35]
	v_mfma_f32_16x16x32_bf16 v[20:23], v[164:167], v[204:207], v[20:23]
	v_mfma_f32_16x16x32_bf16 v[16:19], v[172:175], v[204:207], v[16:19]
	v_mfma_f32_16x16x32_bf16 v[4:7], v[164:167], v[212:215], v[4:7]
	v_mfma_f32_16x16x32_bf16 v[0:3], v[172:175], v[212:215], v[0:3]
	v_mfma_f32_16x16x32_bf16 v[52:55], v[168:171], v[192:195], v[52:55]
	v_mfma_f32_16x16x32_bf16 v[48:51], v[184:187], v[192:195], v[48:51]
	v_mfma_f32_16x16x32_bf16 v[36:39], v[168:171], v[200:203], v[36:39]
	v_mfma_f32_16x16x32_bf16 v[32:35], v[184:187], v[200:203], v[32:35]
	v_mfma_f32_16x16x32_bf16 v[20:23], v[168:171], v[208:211], v[20:23]
	v_mfma_f32_16x16x32_bf16 v[16:19], v[184:187], v[208:211], v[16:19]
	v_mfma_f32_16x16x32_bf16 v[4:7], v[168:171], v[216:219], v[4:7]
	v_mfma_f32_16x16x32_bf16 v[0:3], v[184:187], v[216:219], v[0:3]
	s_barrier
	s_add_i32 s56, s56, 2
	s_add_u32 s30, s30, 0x100
	s_addc_u32 s31, s31, 0
	s_add_u32 s54, s54, 0x100
	s_addc_u32 s55, s55, 0
	s_cmp_gt_u32 s56, 13
	s_cbranch_scc0 .LBB0_2022
	s_and_b64 vcc, exec, s[14:15]
	s_cbranch_vccz .LBB0_2025
	s_barrier

.LBB0_2109:
	ds_read_b128 v[146:149], v157
	ds_read_b128 v[168:171], v157 offset:1024
	ds_read_b128 v[172:175], v157 offset:2048
	ds_read_b128 v[176:179], v157 offset:3072
	ds_read_b128 v[184:187], v159
	ds_read_b128 v[188:191], v159 offset:1024
	ds_read_b128 v[192:195], v159 offset:2048
	ds_read_b128 v[196:199], v159 offset:3072
	s_add_u32 s6, s4, 0xfffc0080
	s_addc_u32 s7, s5, -1
	s_cmp_eq_u32 s63, 12
	s_cselect_b32 s37, s29, s7
	s_cselect_b32 s36, s59, s6
	s_cselect_b32 s7, s27, s62
	s_cselect_b32 s6, s60, s61
	v_lshl_add_u64 v[152:153], s[4:5], 0, v[138:139]
	s_add_i32 m0, s44, 0xc000
	ds_read_b128 v[200:203], v163
	ds_read_b128 v[204:207], v163 offset:1024
	ds_read_b128 v[208:211], v163 offset:2048
	ds_read_b128 v[212:215], v163 offset:3072
	ds_read_b128 v[216:219], v163 offset:4096
	ds_read_b128 v[220:223], v163 offset:5120
	ds_read_b128 v[224:227], v163 offset:6144
	ds_read_b128 v[228:231], v163 offset:7168
	global_load_lds_dwordx4 v[152:153], off
	v_lshl_add_u64 v[152:153], s[4:5], 0, v[140:141]
	s_add_i32 m0, s44, 0xe000
	s_nop 0
	global_load_lds_dwordx4 v[152:153], off
	s_waitcnt vmcnt(8)
	s_waitcnt lgkmcnt(0)
	s_barrier
	s_waitcnt lgkmcnt(0)
	v_mfma_f32_16x16x32_bf16 v[124:127], v[146:149], v[200:203], v[124:127]
	v_mfma_f32_16x16x32_bf16 v[120:123], v[172:175], v[200:203], v[120:123]
	v_mfma_f32_16x16x32_bf16 v[108:111], v[146:149], v[208:211], v[108:111]
	v_mfma_f32_16x16x32_bf16 v[104:107], v[172:175], v[208:211], v[104:107]
	v_mfma_f32_16x16x32_bf16 v[92:95], v[146:149], v[216:219], v[92:95]
	v_mfma_f32_16x16x32_bf16 v[88:91], v[172:175], v[216:219], v[88:91]
	v_mfma_f32_16x16x32_bf16 v[76:79], v[146:149], v[224:227], v[76:79]
	v_mfma_f32_16x16x32_bf16 v[72:75], v[172:175], v[224:227], v[72:75]
	v_mfma_f32_16x16x32_bf16 v[124:127], v[168:171], v[204:207], v[124:127]
	v_mfma_f32_16x16x32_bf16 v[120:123], v[176:179], v[204:207], v[120:123]
	v_mfma_f32_16x16x32_bf16 v[108:111], v[168:171], v[212:215], v[108:111]
	v_mfma_f32_16x16x32_bf16 v[104:107], v[176:179], v[212:215], v[104:107]
	v_mfma_f32_16x16x32_bf16 v[92:95], v[168:171], v[220:223], v[92:95]
	v_mfma_f32_16x16x32_bf16 v[88:91], v[176:179], v[220:223], v[88:91]
	v_mfma_f32_16x16x32_bf16 v[76:79], v[168:171], v[228:231], v[76:79]
	v_mfma_f32_16x16x32_bf16 v[72:75], v[176:179], v[228:231], v[72:75]
	v_mfma_f32_16x16x32_bf16 v[116:119], v[184:187], v[200:203], v[116:119]
	v_mfma_f32_16x16x32_bf16 v[112:115], v[192:195], v[200:203], v[112:115]
	v_mfma_f32_16x16x32_bf16 v[100:103], v[184:187], v[208:211], v[100:103]
	v_mfma_f32_16x16x32_bf16 v[96:99], v[192:195], v[208:211], v[96:99]
	v_mfma_f32_16x16x32_bf16 v[84:87], v[184:187], v[216:219], v[84:87]
	v_mfma_f32_16x16x32_bf16 v[80:83], v[192:195], v[216:219], v[80:83]
	v_mfma_f32_16x16x32_bf16 v[68:71], v[184:187], v[224:227], v[68:71]
	v_mfma_f32_16x16x32_bf16 v[64:67], v[192:195], v[224:227], v[64:67]
	v_mfma_f32_16x16x32_bf16 v[116:119], v[188:191], v[204:207], v[116:119]
	v_mfma_f32_16x16x32_bf16 v[112:115], v[196:199], v[204:207], v[112:115]
	v_mfma_f32_16x16x32_bf16 v[100:103], v[188:191], v[212:215], v[100:103]
	v_mfma_f32_16x16x32_bf16 v[96:99], v[196:199], v[212:215], v[96:99]
	v_mfma_f32_16x16x32_bf16 v[84:87], v[188:191], v[220:223], v[84:87]
	v_mfma_f32_16x16x32_bf16 v[80:83], v[196:199], v[220:223], v[80:83]
	v_mfma_f32_16x16x32_bf16 v[68:71], v[188:191], v[228:231], v[68:71]
	v_mfma_f32_16x16x32_bf16 v[64:67], v[196:199], v[228:231], v[64:67]
	s_barrier
	s_add_i32 s64, s52, s41
	v_lshl_add_u64 v[152:153], s[6:7], 0, v[132:133]
	s_mov_b32 m0, s64
	ds_read_b128 v[200:203], v163 offset:16384
	ds_read_b128 v[204:207], v163 offset:17408
	ds_read_b128 v[208:211], v163 offset:18432
	ds_read_b128 v[212:215], v163 offset:19456
	ds_read_b128 v[216:219], v163 offset:20480
	ds_read_b128 v[220:223], v163 offset:21504
	ds_read_b128 v[224:227], v163 offset:22528
	ds_read_b128 v[228:231], v163 offset:23552
	global_load_lds_dwordx4 v[152:153], off
	s_add_i32 m0, s64, 0x2000
	s_add_u32 s64, s6, 0x40000
	v_lshl_add_u64 v[160:161], s[6:7], 0, v[128:129]
	s_addc_u32 s65, s7, 0
	s_add_i32 s66, s53, s41
	global_load_lds_dwordx4 v[160:161], off
	v_lshl_add_u64 v[180:181], s[64:65], 0, v[132:133]
	s_mov_b32 m0, s66
	v_lshl_add_u64 v[232:233], s[36:37], 0, v[130:131]
	global_load_lds_dwordx4 v[180:181], off
	v_lshl_add_u64 v[180:181], s[64:65], 0, v[128:129]
	s_add_i32 m0, s66, 0x2000
	s_nop 0
	global_load_lds_dwordx4 v[180:181], off
	v_lshl_add_u64 v[180:181], s[36:37], 0, v[134:135]
	s_mov_b32 m0, s44
	s_nop 0
	global_load_lds_dwordx4 v[180:181], off
	s_mov_b32 m0, s45
	s_nop 0
	global_load_lds_dwordx4 v[232:233], off
	s_waitcnt vmcnt(8)
	s_waitcnt lgkmcnt(0)
	s_barrier
	s_waitcnt lgkmcnt(0)
	v_mfma_f32_16x16x32_bf16 v[60:63], v[146:149], v[200:203], v[60:63]
	v_mfma_f32_16x16x32_bf16 v[56:59], v[172:175], v[200:203], v[56:59]
	v_mfma_f32_16x16x32_bf16 v[44:47], v[146:149], v[208:211], v[44:47]
	v_mfma_f32_16x16x32_bf16 v[40:43], v[172:175], v[208:211], v[40:43]
	v_mfma_f32_16x16x32_bf16 v[28:31], v[146:149], v[216:219], v[28:31]
	v_mfma_f32_16x16x32_bf16 v[24:27], v[172:175], v[216:219], v[24:27]
	v_mfma_f32_16x16x32_bf16 v[12:15], v[146:149], v[224:227], v[12:15]
	v_mfma_f32_16x16x32_bf16 v[8:11], v[172:175], v[224:227], v[8:11]
	v_mfma_f32_16x16x32_bf16 v[60:63], v[168:171], v[204:207], v[60:63]
	v_mfma_f32_16x16x32_bf16 v[56:59], v[176:179], v[204:207], v[56:59]
	v_mfma_f32_16x16x32_bf16 v[44:47], v[168:171], v[212:215], v[44:47]
	v_mfma_f32_16x16x32_bf16 v[40:43], v[176:179], v[212:215], v[40:43]
	v_mfma_f32_16x16x32_bf16 v[28:31], v[168:171], v[220:223], v[28:31]
	v_mfma_f32_16x16x32_bf16 v[24:27], v[176:179], v[220:223], v[24:27]
	v_mfma_f32_16x16x32_bf16 v[12:15], v[168:171], v[228:231], v[12:15]
	v_mfma_f32_16x16x32_bf16 v[8:11], v[176:179], v[228:231], v[8:11]
	v_mfma_f32_16x16x32_bf16 v[52:55], v[184:187], v[200:203], v[52:55]
	v_mfma_f32_16x16x32_bf16 v[48:51], v[192:195], v[200:203], v[48:51]
	v_mfma_f32_16x16x32_bf16 v[36:39], v[184:187], v[208:211], v[36:39]
	v_mfma_f32_16x16x32_bf16 v[32:35], v[192:195], v[208:211], v[32:35]
	v_mfma_f32_16x16x32_bf16 v[20:23], v[184:187], v[216:219], v[20:23]
	v_mfma_f32_16x16x32_bf16 v[16:19], v[192:195], v[216:219], v[16:19]
	v_mfma_f32_16x16x32_bf16 v[4:7], v[184:187], v[224:227], v[4:7]
	v_mfma_f32_16x16x32_bf16 v[0:3], v[192:195], v[224:227], v[0:3]
	v_mfma_f32_16x16x32_bf16 v[52:55], v[188:191], v[204:207], v[52:55]
	v_mfma_f32_16x16x32_bf16 v[48:51], v[196:199], v[204:207], v[48:51]
	v_mfma_f32_16x16x32_bf16 v[36:39], v[188:191], v[212:215], v[36:39]
	v_mfma_f32_16x16x32_bf16 v[32:35], v[196:199], v[212:215], v[32:35]
	v_mfma_f32_16x16x32_bf16 v[20:23], v[188:191], v[220:223], v[20:23]
	v_mfma_f32_16x16x32_bf16 v[16:19], v[196:199], v[220:223], v[16:19]
	v_mfma_f32_16x16x32_bf16 v[4:7], v[188:191], v[228:231], v[4:7]
	v_mfma_f32_16x16x32_bf16 v[0:3], v[196:199], v[228:231], v[0:3]
	s_barrier
	s_add_i32 s64, 0, 0x18000
	v_add_u32_e32 v150, s64, v155
	s_add_i32 s65, 0, 0x1c000
	ds_read_b128 v[146:149], v150
	ds_read_b128 v[168:171], v150 offset:1024
	ds_read_b128 v[172:175], v150 offset:2048
	ds_read_b128 v[176:179], v150 offset:3072
	v_add_u32_e32 v150, s65, v155
	ds_read_b128 v[184:187], v150
	ds_read_b128 v[188:191], v150 offset:1024
	ds_read_b128 v[192:195], v150 offset:2048
	ds_read_b128 v[196:199], v150 offset:3072
	s_add_u32 s36, s36, 0x40000
	s_addc_u32 s37, s37, 0
	s_mov_b32 m0, s46
	v_lshl_add_u64 v[234:235], s[36:37], 0, v[134:135]
	ds_read_b128 v[200:203], v163 offset:32768
	ds_read_b128 v[204:207], v163 offset:33792
	ds_read_b128 v[208:211], v163 offset:34816
	ds_read_b128 v[212:215], v163 offset:35840
	ds_read_b128 v[216:219], v163 offset:36864
	ds_read_b128 v[220:223], v163 offset:37888
	ds_read_b128 v[224:227], v163 offset:38912
	ds_read_b128 v[228:231], v163 offset:39936
	global_load_lds_dwordx4 v[234:235], off
	v_lshl_add_u64 v[234:235], s[36:37], 0, v[130:131]
	s_mov_b32 m0, s47
	s_nop 0
	global_load_lds_dwordx4 v[234:235], off
	s_waitcnt vmcnt(8)
	s_waitcnt lgkmcnt(0)
	s_barrier
	s_waitcnt lgkmcnt(0)
	v_mfma_f32_16x16x32_bf16 v[124:127], v[146:149], v[200:203], v[124:127]
	v_mfma_f32_16x16x32_bf16 v[120:123], v[172:175], v[200:203], v[120:123]
	v_mfma_f32_16x16x32_bf16 v[108:111], v[146:149], v[208:211], v[108:111]
	v_mfma_f32_16x16x32_bf16 v[104:107], v[172:175], v[208:211], v[104:107]
	v_mfma_f32_16x16x32_bf16 v[92:95], v[146:149], v[216:219], v[92:95]
	v_mfma_f32_16x16x32_bf16 v[88:91], v[172:175], v[216:219], v[88:91]
	v_mfma_f32_16x16x32_bf16 v[76:79], v[146:149], v[224:227], v[76:79]
	v_mfma_f32_16x16x32_bf16 v[72:75], v[172:175], v[224:227], v[72:75]
	v_mfma_f32_16x16x32_bf16 v[124:127], v[168:171], v[204:207], v[124:127]
	v_mfma_f32_16x16x32_bf16 v[120:123], v[176:179], v[204:207], v[120:123]
	v_mfma_f32_16x16x32_bf16 v[108:111], v[168:171], v[212:215], v[108:111]
	v_mfma_f32_16x16x32_bf16 v[104:107], v[176:179], v[212:215], v[104:107]
	v_mfma_f32_16x16x32_bf16 v[92:95], v[168:171], v[220:223], v[92:95]
	v_mfma_f32_16x16x32_bf16 v[88:91], v[176:179], v[220:223], v[88:91]
	v_mfma_f32_16x16x32_bf16 v[76:79], v[168:171], v[228:231], v[76:79]
	v_mfma_f32_16x16x32_bf16 v[72:75], v[176:179], v[228:231], v[72:75]
	v_mfma_f32_16x16x32_bf16 v[116:119], v[184:187], v[200:203], v[116:119]
	v_mfma_f32_16x16x32_bf16 v[112:115], v[192:195], v[200:203], v[112:115]
	v_mfma_f32_16x16x32_bf16 v[100:103], v[184:187], v[208:211], v[100:103]
	v_mfma_f32_16x16x32_bf16 v[96:99], v[192:195], v[208:211], v[96:99]
	v_mfma_f32_16x16x32_bf16 v[84:87], v[184:187], v[216:219], v[84:87]
	v_mfma_f32_16x16x32_bf16 v[80:83], v[192:195], v[216:219], v[80:83]
	v_mfma_f32_16x16x32_bf16 v[68:71], v[184:187], v[224:227], v[68:71]
	v_mfma_f32_16x16x32_bf16 v[64:67], v[192:195], v[224:227], v[64:67]
	v_mfma_f32_16x16x32_bf16 v[116:119], v[188:191], v[204:207], v[116:119]
	v_mfma_f32_16x16x32_bf16 v[112:115], v[196:199], v[204:207], v[112:115]
	v_mfma_f32_16x16x32_bf16 v[100:103], v[188:191], v[212:215], v[100:103]
	v_mfma_f32_16x16x32_bf16 v[96:99], v[196:199], v[212:215], v[96:99]
	v_mfma_f32_16x16x32_bf16 v[84:87], v[188:191], v[220:223], v[84:87]
	v_mfma_f32_16x16x32_bf16 v[80:83], v[196:199], v[220:223], v[80:83]
	v_mfma_f32_16x16x32_bf16 v[68:71], v[188:191], v[228:231], v[68:71]
	v_mfma_f32_16x16x32_bf16 v[64:67], v[196:199], v[228:231], v[64:67]
	s_barrier
	s_add_i32 s36, s64, s41
	v_lshl_add_u64 v[152:153], v[152:153], 0, s[14:15]
	s_mov_b32 m0, s36
	ds_read_b128 v[200:203], v163 offset:49152
	ds_read_b128 v[204:207], v163 offset:50176
	ds_read_b128 v[208:211], v163 offset:51200
	ds_read_b128 v[212:215], v163 offset:52224
	ds_read_b128 v[216:219], v163 offset:53248
	ds_read_b128 v[220:223], v163 offset:54272
	ds_read_b128 v[224:227], v163 offset:55296
	ds_read_b128 v[228:231], v163 offset:56320
	global_load_lds_dwordx4 v[152:153], off
	s_add_i32 m0, s36, 0x2000
	s_add_u32 s6, s6, 0x40080
	v_lshl_add_u64 v[152:153], v[160:161], 0, s[14:15]
	s_addc_u32 s7, s7, 0
	s_add_i32 s36, s65, s41
	global_load_lds_dwordx4 v[152:153], off
	v_lshl_add_u64 v[152:153], s[6:7], 0, v[132:133]
	s_mov_b32 m0, s36
	s_nop 0
	global_load_lds_dwordx4 v[152:153], off
	v_lshl_add_u64 v[152:153], s[6:7], 0, v[128:129]
	s_add_i32 m0, s36, 0x2000
	s_nop 0
	global_load_lds_dwordx4 v[152:153], off
	v_lshl_add_u64 v[152:153], v[180:181], 0, s[14:15]
	s_mov_b32 m0, s49
	s_nop 0
	global_load_lds_dwordx4 v[152:153], off
	v_lshl_add_u64 v[152:153], v[232:233], 0, s[14:15]
	s_mov_b32 m0, s50
	s_nop 0
	global_load_lds_dwordx4 v[152:153], off
	s_waitcnt vmcnt(8)
	s_waitcnt lgkmcnt(0)
	s_barrier
	s_waitcnt lgkmcnt(0)
	v_mfma_f32_16x16x32_bf16 v[60:63], v[146:149], v[200:203], v[60:63]
	v_mfma_f32_16x16x32_bf16 v[56:59], v[172:175], v[200:203], v[56:59]
	v_mfma_f32_16x16x32_bf16 v[44:47], v[146:149], v[208:211], v[44:47]
	v_mfma_f32_16x16x32_bf16 v[40:43], v[172:175], v[208:211], v[40:43]
	v_mfma_f32_16x16x32_bf16 v[28:31], v[146:149], v[216:219], v[28:31]
	v_mfma_f32_16x16x32_bf16 v[24:27], v[172:175], v[216:219], v[24:27]
	v_mfma_f32_16x16x32_bf16 v[12:15], v[146:149], v[224:227], v[12:15]
	v_mfma_f32_16x16x32_bf16 v[8:11], v[172:175], v[224:227], v[8:11]
	v_mfma_f32_16x16x32_bf16 v[60:63], v[168:171], v[204:207], v[60:63]
	v_mfma_f32_16x16x32_bf16 v[56:59], v[176:179], v[204:207], v[56:59]
	v_mfma_f32_16x16x32_bf16 v[44:47], v[168:171], v[212:215], v[44:47]
	v_mfma_f32_16x16x32_bf16 v[40:43], v[176:179], v[212:215], v[40:43]
	v_mfma_f32_16x16x32_bf16 v[28:31], v[168:171], v[220:223], v[28:31]
	v_mfma_f32_16x16x32_bf16 v[24:27], v[176:179], v[220:223], v[24:27]
	v_mfma_f32_16x16x32_bf16 v[12:15], v[168:171], v[228:231], v[12:15]
	v_mfma_f32_16x16x32_bf16 v[8:11], v[176:179], v[228:231], v[8:11]
	v_mfma_f32_16x16x32_bf16 v[52:55], v[184:187], v[200:203], v[52:55]
	v_mfma_f32_16x16x32_bf16 v[48:51], v[192:195], v[200:203], v[48:51]
	v_mfma_f32_16x16x32_bf16 v[36:39], v[184:187], v[208:211], v[36:39]
	v_mfma_f32_16x16x32_bf16 v[32:35], v[192:195], v[208:211], v[32:35]
	v_mfma_f32_16x16x32_bf16 v[20:23], v[184:187], v[216:219], v[20:23]
	v_mfma_f32_16x16x32_bf16 v[16:19], v[192:195], v[216:219], v[16:19]
	v_mfma_f32_16x16x32_bf16 v[4:7], v[184:187], v[224:227], v[4:7]
	v_mfma_f32_16x16x32_bf16 v[0:3], v[192:195], v[224:227], v[0:3]
	v_mfma_f32_16x16x32_bf16 v[52:55], v[188:191], v[204:207], v[52:55]
	v_mfma_f32_16x16x32_bf16 v[48:51], v[196:199], v[204:207], v[48:51]
	v_mfma_f32_16x16x32_bf16 v[36:39], v[188:191], v[212:215], v[36:39]
	v_mfma_f32_16x16x32_bf16 v[32:35], v[196:199], v[212:215], v[32:35]
	v_mfma_f32_16x16x32_bf16 v[20:23], v[188:191], v[220:223], v[20:23]
	v_mfma_f32_16x16x32_bf16 v[16:19], v[196:199], v[220:223], v[16:19]
	v_mfma_f32_16x16x32_bf16 v[4:7], v[188:191], v[228:231], v[4:7]
	v_mfma_f32_16x16x32_bf16 v[0:3], v[196:199], v[228:231], v[0:3]
	s_barrier
	s_add_i32 s63, s63, 2
	s_add_u32 s4, s4, 0x100
	s_addc_u32 s5, s5, 0
	s_add_u32 s61, s61, 0x100
	s_addc_u32 s62, s62, 0
	s_cmp_gt_u32 s63, 13
	s_cbranch_scc0 .LBB0_2109
	s_and_b64 vcc, exec, s[16:17]
	s_cbranch_vccz .LBB0_2112
	s_barrier

.LBB0_2180:
	ds_read_b128 v[128:131], v181
	ds_read_b128 v[132:135], v181 offset:1024
	ds_read_b128 v[136:139], v181 offset:2048
	ds_read_b128 v[140:143], v181 offset:3072
	ds_read_b128 v[166:169], v182
	ds_read_b128 v[170:173], v182 offset:1024
	ds_read_b128 v[174:177], v182 offset:2048
	ds_read_b128 v[184:187], v182 offset:3072
	s_add_u32 s22, s20, 0xfff00080
	s_addc_u32 s23, s21, -1
	s_cmp_eq_u32 s46, 60
	s_cselect_b32 s25, s13, s23
	s_cselect_b32 s24, s42, s22
	s_cselect_b32 s23, s11, s45
	s_cselect_b32 s22, s43, s44
	v_lshl_add_u64 v[178:179], s[20:21], 0, v[158:159]
	s_add_i32 m0, s31, 0xc000
	ds_read_b128 v[188:191], v183
	ds_read_b128 v[192:195], v183 offset:1024
	ds_read_b128 v[196:199], v183 offset:2048
	ds_read_b128 v[200:203], v183 offset:3072
	ds_read_b128 v[204:207], v183 offset:4096
	ds_read_b128 v[208:211], v183 offset:5120
	ds_read_b128 v[212:215], v183 offset:6144
	ds_read_b128 v[216:219], v183 offset:7168
	global_load_lds_dwordx4 v[178:179], off
	v_lshl_add_u64 v[178:179], s[20:21], 0, v[160:161]
	s_add_i32 m0, s31, 0xe000
	s_nop 0
	global_load_lds_dwordx4 v[178:179], off
	s_waitcnt vmcnt(8)
	s_waitcnt lgkmcnt(0)
	s_barrier
	s_waitcnt lgkmcnt(0)
	v_mfma_f32_16x16x32_bf16 v[124:127], v[128:131], v[188:191], v[124:127]
	v_mfma_f32_16x16x32_bf16 v[120:123], v[136:139], v[188:191], v[120:123]
	v_mfma_f32_16x16x32_bf16 v[108:111], v[128:131], v[196:199], v[108:111]
	v_mfma_f32_16x16x32_bf16 v[104:107], v[136:139], v[196:199], v[104:107]
	v_mfma_f32_16x16x32_bf16 v[92:95], v[128:131], v[204:207], v[92:95]
	v_mfma_f32_16x16x32_bf16 v[88:91], v[136:139], v[204:207], v[88:91]
	v_mfma_f32_16x16x32_bf16 v[76:79], v[128:131], v[212:215], v[76:79]
	v_mfma_f32_16x16x32_bf16 v[72:75], v[136:139], v[212:215], v[72:75]
	v_mfma_f32_16x16x32_bf16 v[124:127], v[132:135], v[192:195], v[124:127]
	v_mfma_f32_16x16x32_bf16 v[120:123], v[140:143], v[192:195], v[120:123]
	v_mfma_f32_16x16x32_bf16 v[108:111], v[132:135], v[200:203], v[108:111]
	v_mfma_f32_16x16x32_bf16 v[104:107], v[140:143], v[200:203], v[104:107]
	v_mfma_f32_16x16x32_bf16 v[92:95], v[132:135], v[208:211], v[92:95]
	v_mfma_f32_16x16x32_bf16 v[88:91], v[140:143], v[208:211], v[88:91]
	v_mfma_f32_16x16x32_bf16 v[76:79], v[132:135], v[216:219], v[76:79]
	v_mfma_f32_16x16x32_bf16 v[72:75], v[140:143], v[216:219], v[72:75]
	v_mfma_f32_16x16x32_bf16 v[116:119], v[166:169], v[188:191], v[116:119]
	v_mfma_f32_16x16x32_bf16 v[112:115], v[174:177], v[188:191], v[112:115]
	v_mfma_f32_16x16x32_bf16 v[100:103], v[166:169], v[196:199], v[100:103]
	v_mfma_f32_16x16x32_bf16 v[96:99], v[174:177], v[196:199], v[96:99]
	v_mfma_f32_16x16x32_bf16 v[84:87], v[166:169], v[204:207], v[84:87]
	v_mfma_f32_16x16x32_bf16 v[80:83], v[174:177], v[204:207], v[80:83]
	v_mfma_f32_16x16x32_bf16 v[68:71], v[166:169], v[212:215], v[68:71]
	v_mfma_f32_16x16x32_bf16 v[64:67], v[174:177], v[212:215], v[64:67]
	v_mfma_f32_16x16x32_bf16 v[116:119], v[170:173], v[192:195], v[116:119]
	v_mfma_f32_16x16x32_bf16 v[112:115], v[184:187], v[192:195], v[112:115]
	v_mfma_f32_16x16x32_bf16 v[100:103], v[170:173], v[200:203], v[100:103]
	v_mfma_f32_16x16x32_bf16 v[96:99], v[184:187], v[200:203], v[96:99]
	v_mfma_f32_16x16x32_bf16 v[84:87], v[170:173], v[208:211], v[84:87]
	v_mfma_f32_16x16x32_bf16 v[80:83], v[184:187], v[208:211], v[80:83]
	v_mfma_f32_16x16x32_bf16 v[68:71], v[170:173], v[216:219], v[68:71]
	v_mfma_f32_16x16x32_bf16 v[64:67], v[184:187], v[216:219], v[64:67]
	s_barrier
	s_add_i32 s47, s40, s28
	v_lshl_add_u64 v[178:179], s[22:23], 0, v[148:149]
	s_mov_b32 m0, s47
	ds_read_b128 v[188:191], v183 offset:16384
	ds_read_b128 v[192:195], v183 offset:17408
	ds_read_b128 v[196:199], v183 offset:18432
	ds_read_b128 v[200:203], v183 offset:19456
	ds_read_b128 v[204:207], v183 offset:20480
	ds_read_b128 v[208:211], v183 offset:21504
	ds_read_b128 v[212:215], v183 offset:22528
	ds_read_b128 v[216:219], v183 offset:23552
	global_load_lds_dwordx4 v[178:179], off
	s_add_i32 m0, s47, 0x2000
	s_add_u32 s48, s22, 0x100000
	v_lshl_add_u64 v[220:221], s[22:23], 0, v[144:145]
	s_addc_u32 s49, s23, 0
	s_add_i32 s47, s41, s28
	global_load_lds_dwordx4 v[220:221], off
	v_lshl_add_u64 v[222:223], s[48:49], 0, v[148:149]
	s_mov_b32 m0, s47
	v_lshl_add_u64 v[224:225], s[24:25], 0, v[146:147]
	global_load_lds_dwordx4 v[222:223], off
	v_lshl_add_u64 v[222:223], s[48:49], 0, v[144:145]
	s_add_i32 m0, s47, 0x2000
	s_nop 0
	global_load_lds_dwordx4 v[222:223], off
	v_lshl_add_u64 v[222:223], s[24:25], 0, v[150:151]
	s_mov_b32 m0, s31
	s_nop 0
	global_load_lds_dwordx4 v[222:223], off
	s_mov_b32 m0, s33
	s_nop 0
	global_load_lds_dwordx4 v[224:225], off
	s_waitcnt vmcnt(8)
	s_waitcnt lgkmcnt(0)
	s_barrier
	s_waitcnt lgkmcnt(0)
	v_mfma_f32_16x16x32_bf16 v[60:63], v[128:131], v[188:191], v[60:63]
	v_mfma_f32_16x16x32_bf16 v[56:59], v[136:139], v[188:191], v[56:59]
	v_mfma_f32_16x16x32_bf16 v[44:47], v[128:131], v[196:199], v[44:47]
	v_mfma_f32_16x16x32_bf16 v[40:43], v[136:139], v[196:199], v[40:43]
	v_mfma_f32_16x16x32_bf16 v[32:35], v[128:131], v[204:207], v[32:35]
	v_mfma_f32_16x16x32_bf16 v[24:27], v[136:139], v[204:207], v[24:27]
	v_mfma_f32_16x16x32_bf16 v[16:19], v[128:131], v[212:215], v[16:19]
	v_mfma_f32_16x16x32_bf16 v[8:11], v[136:139], v[212:215], v[8:11]
	v_mfma_f32_16x16x32_bf16 v[60:63], v[132:135], v[192:195], v[60:63]
	v_mfma_f32_16x16x32_bf16 v[56:59], v[140:143], v[192:195], v[56:59]
	v_mfma_f32_16x16x32_bf16 v[44:47], v[132:135], v[200:203], v[44:47]
	v_mfma_f32_16x16x32_bf16 v[40:43], v[140:143], v[200:203], v[40:43]
	v_mfma_f32_16x16x32_bf16 v[32:35], v[132:135], v[208:211], v[32:35]
	v_mfma_f32_16x16x32_bf16 v[24:27], v[140:143], v[208:211], v[24:27]
	v_mfma_f32_16x16x32_bf16 v[16:19], v[132:135], v[216:219], v[16:19]
	v_mfma_f32_16x16x32_bf16 v[8:11], v[140:143], v[216:219], v[8:11]
	v_mfma_f32_16x16x32_bf16 v[52:55], v[166:169], v[188:191], v[52:55]
	v_mfma_f32_16x16x32_bf16 v[48:51], v[174:177], v[188:191], v[48:51]
	v_mfma_f32_16x16x32_bf16 v[36:39], v[166:169], v[196:199], v[36:39]
	v_mfma_f32_16x16x32_bf16 v[28:31], v[174:177], v[196:199], v[28:31]
	v_mfma_f32_16x16x32_bf16 v[20:23], v[166:169], v[204:207], v[20:23]
	v_mfma_f32_16x16x32_bf16 v[12:15], v[174:177], v[204:207], v[12:15]
	v_mfma_f32_16x16x32_bf16 v[4:7], v[166:169], v[212:215], v[4:7]
	v_mfma_f32_16x16x32_bf16 v[0:3], v[174:177], v[212:215], v[0:3]
	v_mfma_f32_16x16x32_bf16 v[52:55], v[170:173], v[192:195], v[52:55]
	v_mfma_f32_16x16x32_bf16 v[48:51], v[184:187], v[192:195], v[48:51]
	v_mfma_f32_16x16x32_bf16 v[36:39], v[170:173], v[200:203], v[36:39]
	v_mfma_f32_16x16x32_bf16 v[28:31], v[184:187], v[200:203], v[28:31]
	v_mfma_f32_16x16x32_bf16 v[20:23], v[170:173], v[208:211], v[20:23]
	v_mfma_f32_16x16x32_bf16 v[12:15], v[184:187], v[208:211], v[12:15]
	v_mfma_f32_16x16x32_bf16 v[4:7], v[170:173], v[216:219], v[4:7]
	v_mfma_f32_16x16x32_bf16 v[0:3], v[184:187], v[216:219], v[0:3]
	s_barrier
	s_add_i32 s47, 0, 0x18000
	s_add_i32 s48, 0, 0x1c000
	v_add_u32_e32 v140, s47, v180
	v_add_u32_e32 v152, s48, v180
	ds_read_b128 v[128:131], v140
	ds_read_b128 v[132:135], v140 offset:1024
	ds_read_b128 v[136:139], v140 offset:2048
	ds_read_b128 v[140:143], v140 offset:3072
	ds_read_b128 v[166:169], v152
	ds_read_b128 v[170:173], v152 offset:1024
	ds_read_b128 v[174:177], v152 offset:2048
	ds_read_b128 v[184:187], v152 offset:3072
	s_add_u32 s24, s24, 0x100000
	s_addc_u32 s25, s25, 0
	s_mov_b32 m0, s34
	v_lshl_add_u64 v[226:227], s[24:25], 0, v[150:151]
	ds_read_b128 v[188:191], v183 offset:32768
	ds_read_b128 v[192:195], v183 offset:33792
	ds_read_b128 v[196:199], v183 offset:34816
	ds_read_b128 v[200:203], v183 offset:35840
	ds_read_b128 v[204:207], v183 offset:36864
	ds_read_b128 v[208:211], v183 offset:37888
	ds_read_b128 v[212:215], v183 offset:38912
	ds_read_b128 v[216:219], v183 offset:39936
	global_load_lds_dwordx4 v[226:227], off
	v_lshl_add_u64 v[226:227], s[24:25], 0, v[146:147]
	s_mov_b32 m0, s35
	s_nop 0
	global_load_lds_dwordx4 v[226:227], off
	s_waitcnt vmcnt(8)
	s_waitcnt lgkmcnt(0)
	s_barrier
	s_waitcnt lgkmcnt(0)
	v_mfma_f32_16x16x32_bf16 v[124:127], v[128:131], v[188:191], v[124:127]
	v_mfma_f32_16x16x32_bf16 v[120:123], v[136:139], v[188:191], v[120:123]
	v_mfma_f32_16x16x32_bf16 v[108:111], v[128:131], v[196:199], v[108:111]
	v_mfma_f32_16x16x32_bf16 v[104:107], v[136:139], v[196:199], v[104:107]
	v_mfma_f32_16x16x32_bf16 v[92:95], v[128:131], v[204:207], v[92:95]
	v_mfma_f32_16x16x32_bf16 v[88:91], v[136:139], v[204:207], v[88:91]
	v_mfma_f32_16x16x32_bf16 v[76:79], v[128:131], v[212:215], v[76:79]
	v_mfma_f32_16x16x32_bf16 v[72:75], v[136:139], v[212:215], v[72:75]
	v_mfma_f32_16x16x32_bf16 v[124:127], v[132:135], v[192:195], v[124:127]
	v_mfma_f32_16x16x32_bf16 v[120:123], v[140:143], v[192:195], v[120:123]
	v_mfma_f32_16x16x32_bf16 v[108:111], v[132:135], v[200:203], v[108:111]
	v_mfma_f32_16x16x32_bf16 v[104:107], v[140:143], v[200:203], v[104:107]
	v_mfma_f32_16x16x32_bf16 v[92:95], v[132:135], v[208:211], v[92:95]
	v_mfma_f32_16x16x32_bf16 v[88:91], v[140:143], v[208:211], v[88:91]
	v_mfma_f32_16x16x32_bf16 v[76:79], v[132:135], v[216:219], v[76:79]
	v_mfma_f32_16x16x32_bf16 v[72:75], v[140:143], v[216:219], v[72:75]
	v_mfma_f32_16x16x32_bf16 v[116:119], v[166:169], v[188:191], v[116:119]
	v_mfma_f32_16x16x32_bf16 v[112:115], v[174:177], v[188:191], v[112:115]
	v_mfma_f32_16x16x32_bf16 v[100:103], v[166:169], v[196:199], v[100:103]
	v_mfma_f32_16x16x32_bf16 v[96:99], v[174:177], v[196:199], v[96:99]
	v_mfma_f32_16x16x32_bf16 v[84:87], v[166:169], v[204:207], v[84:87]
	v_mfma_f32_16x16x32_bf16 v[80:83], v[174:177], v[204:207], v[80:83]
	v_mfma_f32_16x16x32_bf16 v[68:71], v[166:169], v[212:215], v[68:71]
	v_mfma_f32_16x16x32_bf16 v[64:67], v[174:177], v[212:215], v[64:67]
	v_mfma_f32_16x16x32_bf16 v[116:119], v[170:173], v[192:195], v[116:119]
	v_mfma_f32_16x16x32_bf16 v[112:115], v[184:187], v[192:195], v[112:115]
	v_mfma_f32_16x16x32_bf16 v[100:103], v[170:173], v[200:203], v[100:103]
	v_mfma_f32_16x16x32_bf16 v[96:99], v[184:187], v[200:203], v[96:99]
	v_mfma_f32_16x16x32_bf16 v[84:87], v[170:173], v[208:211], v[84:87]
	v_mfma_f32_16x16x32_bf16 v[80:83], v[184:187], v[208:211], v[80:83]
	v_mfma_f32_16x16x32_bf16 v[68:71], v[170:173], v[216:219], v[68:71]
	v_mfma_f32_16x16x32_bf16 v[64:67], v[184:187], v[216:219], v[64:67]
	s_barrier
	s_add_i32 s24, s47, s28
	v_lshl_add_u64 v[178:179], v[178:179], 0, s[6:7]
	s_mov_b32 m0, s24
	ds_read_b128 v[188:191], v183 offset:49152
	ds_read_b128 v[192:195], v183 offset:50176
	ds_read_b128 v[196:199], v183 offset:51200
	ds_read_b128 v[200:203], v183 offset:52224
	ds_read_b128 v[204:207], v183 offset:53248
	ds_read_b128 v[208:211], v183 offset:54272
	ds_read_b128 v[212:215], v183 offset:55296
	ds_read_b128 v[216:219], v183 offset:56320
	global_load_lds_dwordx4 v[178:179], off
	s_add_i32 m0, s24, 0x2000
	s_add_u32 s22, s22, 0x100080
	v_lshl_add_u64 v[178:179], v[220:221], 0, s[6:7]
	s_addc_u32 s23, s23, 0
	s_add_i32 s24, s48, s28
	global_load_lds_dwordx4 v[178:179], off
	v_lshl_add_u64 v[178:179], s[22:23], 0, v[148:149]
	s_mov_b32 m0, s24
	s_nop 0
	global_load_lds_dwordx4 v[178:179], off
	v_lshl_add_u64 v[178:179], s[22:23], 0, v[144:145]
	s_add_i32 m0, s24, 0x2000
	s_nop 0
	global_load_lds_dwordx4 v[178:179], off
	v_lshl_add_u64 v[178:179], v[222:223], 0, s[6:7]
	s_mov_b32 m0, s37
	s_nop 0
	global_load_lds_dwordx4 v[178:179], off
	v_lshl_add_u64 v[178:179], v[224:225], 0, s[6:7]
	s_mov_b32 m0, s38
	s_nop 0
	global_load_lds_dwordx4 v[178:179], off
	s_waitcnt vmcnt(8)
	s_waitcnt lgkmcnt(0)
	s_barrier
	s_waitcnt lgkmcnt(0)
	v_mfma_f32_16x16x32_bf16 v[60:63], v[128:131], v[188:191], v[60:63]
	v_mfma_f32_16x16x32_bf16 v[56:59], v[136:139], v[188:191], v[56:59]
	v_mfma_f32_16x16x32_bf16 v[44:47], v[128:131], v[196:199], v[44:47]
	v_mfma_f32_16x16x32_bf16 v[40:43], v[136:139], v[196:199], v[40:43]
	v_mfma_f32_16x16x32_bf16 v[32:35], v[128:131], v[204:207], v[32:35]
	v_mfma_f32_16x16x32_bf16 v[24:27], v[136:139], v[204:207], v[24:27]
	v_mfma_f32_16x16x32_bf16 v[16:19], v[128:131], v[212:215], v[16:19]
	v_mfma_f32_16x16x32_bf16 v[8:11], v[136:139], v[212:215], v[8:11]
	v_mfma_f32_16x16x32_bf16 v[60:63], v[132:135], v[192:195], v[60:63]
	v_mfma_f32_16x16x32_bf16 v[56:59], v[140:143], v[192:195], v[56:59]
	v_mfma_f32_16x16x32_bf16 v[44:47], v[132:135], v[200:203], v[44:47]
	v_mfma_f32_16x16x32_bf16 v[40:43], v[140:143], v[200:203], v[40:43]
	v_mfma_f32_16x16x32_bf16 v[32:35], v[132:135], v[208:211], v[32:35]
	v_mfma_f32_16x16x32_bf16 v[24:27], v[140:143], v[208:211], v[24:27]
	v_mfma_f32_16x16x32_bf16 v[16:19], v[132:135], v[216:219], v[16:19]
	v_mfma_f32_16x16x32_bf16 v[8:11], v[140:143], v[216:219], v[8:11]
	v_mfma_f32_16x16x32_bf16 v[52:55], v[166:169], v[188:191], v[52:55]
	v_mfma_f32_16x16x32_bf16 v[48:51], v[174:177], v[188:191], v[48:51]
	v_mfma_f32_16x16x32_bf16 v[36:39], v[166:169], v[196:199], v[36:39]
	v_mfma_f32_16x16x32_bf16 v[28:31], v[174:177], v[196:199], v[28:31]
	v_mfma_f32_16x16x32_bf16 v[20:23], v[166:169], v[204:207], v[20:23]
	v_mfma_f32_16x16x32_bf16 v[12:15], v[174:177], v[204:207], v[12:15]
	v_mfma_f32_16x16x32_bf16 v[4:7], v[166:169], v[212:215], v[4:7]
	v_mfma_f32_16x16x32_bf16 v[0:3], v[174:177], v[212:215], v[0:3]
	v_mfma_f32_16x16x32_bf16 v[52:55], v[170:173], v[192:195], v[52:55]
	v_mfma_f32_16x16x32_bf16 v[48:51], v[184:187], v[192:195], v[48:51]
	v_mfma_f32_16x16x32_bf16 v[36:39], v[170:173], v[200:203], v[36:39]
	v_mfma_f32_16x16x32_bf16 v[28:31], v[184:187], v[200:203], v[28:31]
	v_mfma_f32_16x16x32_bf16 v[20:23], v[170:173], v[208:211], v[20:23]
	v_mfma_f32_16x16x32_bf16 v[12:15], v[184:187], v[208:211], v[12:15]
	v_mfma_f32_16x16x32_bf16 v[4:7], v[170:173], v[216:219], v[4:7]
	v_mfma_f32_16x16x32_bf16 v[0:3], v[184:187], v[216:219], v[0:3]
	s_barrier
	s_add_i32 s46, s46, 2
	s_add_u32 s20, s20, 0x100
	s_addc_u32 s21, s21, 0
	s_add_u32 s44, s44, 0x100
	s_addc_u32 s45, s45, 0
	s_cmp_gt_u32 s46, 61
	s_cbranch_scc0 .LBB0_2180
	s_and_b64 vcc, exec, s[8:9]
	s_cbranch_vccz .LBB0_2183
	s_barrier
